# stack16: stack14 + back-edge rotation of the four GEMM K-loops (stage-select address block moved in front of the loop-back barrier)
# speedup vs baseline: 1.0175x; 1.0175x over previous
; #define WAIT_V0() asm volatile("s_waitcnt vmcnt(0)" ::: "memory")
; #define G_LANE_SETUP() \
;     int tid_ = threadIdx.x; \
;     asm volatile("" : "+v"(tid_));    \
;     const int wid = tid_ >> 6, lane = tid_ & 63, wr = wid >> 2, wc = wid & 3, fr = lane & 15, fq = lane >> 4; \
;     unsigned soff[4];        \
;     _Pragma("unroll") for (int i = 0; i < 4; ++i) { int sR, sC; stage_rc2(wid * 1024 + i * 8192 + lane * 16, sR, sC); soff[i] = (unsigned)(sR * K + sC) * 2u; }
; #define G_SB0() __builtin_amdgcn_sched_barrier(0)
; template <int EK>
; DI void gemm_stream(const Params& p, int l, const bf16_t* __restrict__ A, const bf16_t* __restrict__ Bt, int M, int N, int K, ldsp_t shm) {
;     ...
;     const int nt = K / 64;
;     int pm, pn;
;     tile_coords(L, nM, nN, pm, pn);
;     const bf16_t* Ab = A + (size_t)pm * 256 * K;
;     const bf16_t* Bb = Bt + (size_t)pn * 256 * K;
;     { G_LANE_SETUP(); (void)wr; (void)wc; (void)fr; (void)fq; G_STAGE(Ab, Bb, 0, 0); WAIT_V0(); __syncthreads(); }
;     while (true) {
;         G_LANE_SETUP();
;         const int aoff = lds_byte2(wr * 128 + fr, fq * 8), boff = lds_byte2(wc * 64 + fr, fq * 8);
;         f32x4 acc[8][4];
; #pragma unroll
;         for (int m = 0; m < 8; ++m)
; #pragma unroll
;             for (int n = 0; n < 4; ++n) acc[m][n] = (f32x4){0.f, 0.f, 0.f, 0.f};
;         const int Ln = L + gridDim.x;
;         const bool has_next = Ln < nwg;
;         int pm2 = pm, pn2 = pn;
;         if (has_next) tile_coords(Ln, nM, nN, pm2, pn2);
;         const bf16_t* Ab2 = A + (size_t)pm2 * 256 * K;
;         const bf16_t* Bb2 = Bt + (size_t)pn2 * 256 * K;
;         bf16x8 Aa[4], Ab_[4], Bk0[4], Bk1[4];
;     ...
;         for (int t = 0; t < nt; ++t) {
;             const int cur = t & 1;
;             G_RDA(Aa, cur, 0, 0); G_RDB(Bk0, cur, 0);
;             if (t + 1 < nt) G_STAGE_B(Bb, cur ^ 1, t + 1);
;             else if (has_next) G_STAGE_B(Bb2, cur ^ 1, 0);
;             G_SB0();
;             if (t > 0) G_MMA(Ab_, Bk1, 1);
;             G_SB0();
;             if (t + 1 < nt) G_STAGE_A(Ab, cur ^ 1, t + 1);
;             else if (has_next) G_STAGE_A(Ab2, cur ^ 1, 0);
;             G_RDA(Ab_, cur, 0, 1);
;             G_MMA(Aa, Bk0, 0); G_SB0();
;             G_RDA(Aa, cur, 1, 0); G_RDB(Bk1, cur, 1);
;             G_MMA(Ab_, Bk0, 1); G_SB0();
;             G_RDA(Ab_, cur, 1, 1);
;             G_MMA(Aa, Bk1, 0); G_SB0();
.LBB0_110:
	v_lshlrev_b32_e32 v0, 4, v160
	v_and_b32_e32 v1, 32, v160
	v_bfe_u32 v161, v160, 2, 4
	v_and_b32_e32 v190, 64, v160
	v_bitop3_b32 v191, v0, v1, 48 bitop3:0x6c
	v_lshrrev_b32_e32 v2, 3, v160
	v_or_b32_e32 v1, v191, v190
	v_and_or_b32 v2, v2, s86, v161
	v_add_u32_e32 v200, 0x2000, v0
	v_lshl_or_b32 v192, v2, 11, v1
	v_lshrrev_b32_e32 v2, 7, v200
	v_and_or_b32 v2, v2, s86, v161
	v_add_u32_e32 v201, 0x4000, v0
	v_add_u32_e32 v221, 0x6000, v0
	v_and_b32_e32 v220, 0xfffffc00, v0
	v_lshl_or_b32 v194, v2, 11, v1
	v_lshrrev_b32_e32 v2, 7, v201
	v_lshrrev_b32_e32 v0, 7, v221
	v_and_or_b32 v2, v2, s86, v161
	v_and_or_b32 v0, v0, s86, v161
	v_lshl_or_b32 v196, v2, 11, v1
	v_lshl_or_b32 v198, v0, 11, v1
	v_lshlrev_b32_e32 v1, 6, v160
	v_lshlrev_b32_e32 v4, 2, v160
	v_and_b32_e32 v0, 48, v160
	v_and_b32_e32 v2, 0x3c0, v1
	v_and_b32_e32 v4, 32, v4
	v_bitop3_b32 v0, v2, v4, v0 bitop3:0x36
	s_movk_i32 s4, 0xc000
	v_and_or_b32 v218, v1, s4, v0
	s_add_u32 s4, s9, s38
	s_addc_u32 s5, s45, s39
	v_add_u32_e32 v34, 0x18000, v220
	v_lshl_add_u64 v[32:33], s[4:5], 0, v[192:193]
	v_readfirstlane_b32 s35, v34
	v_lshlrev_b32_e32 v3, 7, v160
	v_lshl_add_u64 v[32:33], v[32:33], 0, s[0:1]
	s_mov_b32 m0, s35
	v_mov_b32_e32 v195, v193
	v_add_u32_e32 v34, 0x1a000, v220
	v_and_or_b32 v219, v3, s28, v0
	ds_read_b128 v[0:3], v218
	ds_read_b128 v[4:7], v218 offset:2048
	ds_read_b128 v[8:11], v218 offset:4096
	ds_read_b128 v[12:15], v218 offset:6144
	ds_read_b128 v[16:19], v219 offset:32768
	ds_read_b128 v[20:23], v219 offset:34816
	ds_read_b128 v[24:27], v219 offset:36864
	ds_read_b128 v[28:31], v219 offset:38912
	global_load_lds_dwordx4 v[32:33], off
	v_lshl_add_u64 v[32:33], s[4:5], 0, v[194:195]
	v_readfirstlane_b32 s35, v34
	v_lshl_add_u64 v[32:33], v[32:33], 0, s[0:1]
	s_mov_b32 m0, s35
	v_mov_b32_e32 v197, v193
	v_add_u32_e32 v34, 0x1c000, v220
	global_load_lds_dwordx4 v[32:33], off
	v_lshl_add_u64 v[32:33], s[4:5], 0, v[196:197]
	v_readfirstlane_b32 s35, v34
	v_lshl_add_u64 v[32:33], v[32:33], 0, s[0:1]
	s_mov_b32 m0, s35
	v_mov_b32_e32 v199, v193
	v_add_u32_e32 v34, 0x1e000, v220
	global_load_lds_dwordx4 v[32:33], off
	v_lshl_add_u64 v[32:33], s[4:5], 0, v[198:199]
	v_readfirstlane_b32 s4, v34
	v_lshl_add_u64 v[32:33], v[32:33], 0, s[0:1]
	s_mov_b32 m0, s4
	s_nop 0
	global_load_lds_dwordx4 v[32:33], off
	s_add_u32 s4, s82, s40
	s_addc_u32 s5, s83, s41
	v_add_u32_e32 v34, 0x10000, v220
	v_lshl_add_u64 v[32:33], s[4:5], 0, v[192:193]
	v_readfirstlane_b32 s35, v34
	v_lshl_add_u64 v[32:33], v[32:33], 0, s[0:1]
	s_mov_b32 m0, s35
	v_add_u32_e32 v34, 0x12000, v220
	global_load_lds_dwordx4 v[32:33], off
	v_lshl_add_u64 v[32:33], s[4:5], 0, v[194:195]
	v_readfirstlane_b32 s35, v34
	v_lshl_add_u64 v[32:33], v[32:33], 0, s[0:1]
	s_mov_b32 m0, s35
	v_add_u32_e32 v34, 0x14000, v220
	global_load_lds_dwordx4 v[32:33], off
	v_lshl_add_u64 v[32:33], s[4:5], 0, v[196:197]
	v_readfirstlane_b32 s35, v34
	v_lshl_add_u64 v[32:33], v[32:33], 0, s[0:1]
	s_mov_b32 m0, s35
	v_add_u32_e32 v34, 0x16000, v220
	global_load_lds_dwordx4 v[32:33], off
	v_lshl_add_u64 v[32:33], s[4:5], 0, v[198:199]
	v_readfirstlane_b32 s4, v34
	v_lshl_add_u64 v[32:33], v[32:33], 0, s[0:1]
	s_mov_b32 m0, s4
	s_mov_b32 s35, 0x10000
	global_load_lds_dwordx4 v[32:33], off
	ds_read_b128 v[32:35], v218 offset:8192
	ds_read_b128 v[36:39], v218 offset:10240
	ds_read_b128 v[40:43], v218 offset:12288
	ds_read_b128 v[44:47], v218 offset:14336
	s_setprio 1
	s_waitcnt lgkmcnt(0)
	v_mfma_f32_16x16x32_bf16 v[48:51], v[16:19], v[0:3], 0
	v_mfma_f32_16x16x32_bf16 v[52:55], v[20:23], v[0:3], 0
	v_mfma_f32_16x16x32_bf16 v[162:165], v[24:27], v[0:3], 0
	v_mfma_f32_16x16x32_bf16 v[0:3], v[28:31], v[0:3], 0
	v_mfma_f32_16x16x32_bf16 v[166:169], v[16:19], v[4:7], 0
	v_mfma_f32_16x16x32_bf16 v[170:173], v[20:23], v[4:7], 0
	v_mfma_f32_16x16x32_bf16 v[174:177], v[24:27], v[4:7], 0
	v_mfma_f32_16x16x32_bf16 v[4:7], v[28:31], v[4:7], 0
	v_mfma_f32_16x16x32_bf16 v[178:181], v[16:19], v[8:11], 0
	v_mfma_f32_16x16x32_bf16 v[182:185], v[20:23], v[8:11], 0
	v_mfma_f32_16x16x32_bf16 v[186:189], v[24:27], v[8:11], 0
	v_mfma_f32_16x16x32_bf16 v[8:11], v[28:31], v[8:11], 0
	v_mfma_f32_16x16x32_bf16 v[204:207], v[16:19], v[12:15], 0
	v_mfma_f32_16x16x32_bf16 v[210:213], v[20:23], v[12:15], 0
	v_mfma_f32_16x16x32_bf16 v[214:217], v[24:27], v[12:15], 0
	v_mfma_f32_16x16x32_bf16 v[222:225], v[28:31], v[12:15], 0
	s_setprio 0
	ds_read_b128 v[12:15], v218 offset:1024
	ds_read_b128 v[226:229], v218 offset:3072
	ds_read_b128 v[230:233], v218 offset:5120
	ds_read_b128 v[234:237], v218 offset:7168
	ds_read_b128 v[64:67], v219 offset:33792
	ds_read_b128 v[68:71], v219 offset:35840
	ds_read_b128 v[76:79], v219 offset:37888
	ds_read_b128 v[72:75], v219 offset:39936
	s_setprio 1
	v_mfma_f32_16x16x32_bf16 v[128:131], v[16:19], v[32:35], 0
	v_mfma_f32_16x16x32_bf16 v[124:127], v[20:23], v[32:35], 0
	v_mfma_f32_16x16x32_bf16 v[120:123], v[24:27], v[32:35], 0
	v_mfma_f32_16x16x32_bf16 v[116:119], v[28:31], v[32:35], 0
	v_mfma_f32_16x16x32_bf16 v[112:115], v[16:19], v[36:39], 0
	v_mfma_f32_16x16x32_bf16 v[108:111], v[20:23], v[36:39], 0
	v_mfma_f32_16x16x32_bf16 v[104:107], v[24:27], v[36:39], 0
	v_mfma_f32_16x16x32_bf16 v[100:103], v[28:31], v[36:39], 0
	v_mfma_f32_16x16x32_bf16 v[96:99], v[16:19], v[40:43], 0
	v_mfma_f32_16x16x32_bf16 v[92:95], v[20:23], v[40:43], 0
	v_mfma_f32_16x16x32_bf16 v[88:91], v[24:27], v[40:43], 0
	v_mfma_f32_16x16x32_bf16 v[84:87], v[28:31], v[40:43], 0
	v_mfma_f32_16x16x32_bf16 v[132:135], v[16:19], v[44:47], 0
	v_mfma_f32_16x16x32_bf16 v[136:139], v[20:23], v[44:47], 0
	v_mfma_f32_16x16x32_bf16 v[140:143], v[24:27], v[44:47], 0
	v_mfma_f32_16x16x32_bf16 v[80:83], v[28:31], v[44:47], 0
	s_setprio 0
	ds_read_b128 v[156:159], v218 offset:9216
	ds_read_b128 v[152:155], v218 offset:11264
	ds_read_b128 v[148:151], v218 offset:13312
	ds_read_b128 v[144:147], v218 offset:15360
	s_setprio 1
	s_waitcnt lgkmcnt(0)
; #define WAIT_V0() asm volatile("s_waitcnt vmcnt(0)" ::: "memory")
; #define G_STAGE_A(Ap, buf, kt) do { const char* ab_ = (const char*)(Ap) + (size_t)(kt) * 128; \
;       _Pragma("unroll") for (int i = 0; i < 4; ++i) \
;         __builtin_amdgcn_global_load_lds((const unsigned*)(ab_ + soff[i]), (LDSP unsigned*)(G_SA(buf) + wid * 1024 + i * 8192), 16, 0, 0); } while (0)
; #define G_STAGE_B(Bp, buf, kt) do { const char* bb_ = (const char*)(Bp) + (size_t)(kt) * 128; \
;       _Pragma("unroll") for (int i = 0; i < 4; ++i) \
;         __builtin_amdgcn_global_load_lds((const unsigned*)(bb_ + soff[i]), (LDSP unsigned*)(G_SB(buf) + wid * 1024 + i * 8192), 16, 0, 0); } while (0)
; #define G_RDA(AF, buf, ks, mh) do { _Pragma("unroll") for (int m = 0; m < 4; ++m) AF[m] = *(const LDSP bf16x8*)(G_SA(buf) + aoff + ((mh) * 4 + m) * 2048 + (ks) * 1024); } while (0)
; #define G_RDB(BF, buf, ks) do { _Pragma("unroll") for (int n = 0; n < 4; ++n) BF[n] = *(const LDSP bf16x8*)(G_SB(buf) + boff + n * 2048 + (ks) * 1024); } while (0)
; #define G_MMA(AF, BF, mh) do { __builtin_amdgcn_s_setprio(1); \
;             _Pragma("unroll") for (int m = 0; m < 4; ++m) _Pragma("unroll") for (int n = 0; n < 4; ++n) \
;                 acc[(mh) * 4 + m][n] = __builtin_amdgcn_mfma_f32_16x16x32_bf16(BF[n], AF[m], acc[(mh) * 4 + m][n], 0, 0, 0); \
;             __builtin_amdgcn_s_setprio(0); } while (0)
; template <int EK>
; DI void gemm_stream(const Params& p, int l, const bf16_t* __restrict__ A, const bf16_t* __restrict__ Bt, int M, int N, int K, ldsp_t shm) {
;     ...
;         for (int t = 0; t < nt; ++t) {
;             const int cur = t & 1;
;             G_RDA(Aa, cur, 0, 0); G_RDB(Bk0, cur, 0);
;             if (t + 1 < nt) G_STAGE_B(Bb, cur ^ 1, t + 1);
;             else if (has_next) G_STAGE_B(Bb2, cur ^ 1, 0);
;             G_SB0();
;             if (t > 0) G_MMA(Ab_, Bk1, 1);
;             G_SB0();
;             if (t + 1 < nt) G_STAGE_A(Ab, cur ^ 1, t + 1);
;             else if (has_next) G_STAGE_A(Ab2, cur ^ 1, 0);
;             G_RDA(Ab_, cur, 0, 1);
;             G_MMA(Aa, Bk0, 0); G_SB0();
;             G_RDA(Aa, cur, 1, 0); G_RDB(Bk1, cur, 1);
;             G_MMA(Ab_, Bk0, 1); G_SB0();
;             G_RDA(Ab_, cur, 1, 1);
;             G_MMA(Aa, Bk1, 0); G_SB0();
;             asm volatile("s_waitcnt lgkmcnt(0)" ::: "memory");
;             WAIT_V0(); __syncthreads();
;         }
	v_mfma_f32_16x16x32_bf16 v[60:63], v[64:67], v[12:15], v[48:51]
	v_mfma_f32_16x16x32_bf16 v[56:59], v[68:71], v[12:15], v[52:55]
	v_mfma_f32_16x16x32_bf16 v[52:55], v[76:79], v[12:15], v[162:165]
	v_mfma_f32_16x16x32_bf16 v[48:51], v[72:75], v[12:15], v[0:3]
	v_mfma_f32_16x16x32_bf16 v[44:47], v[64:67], v[226:229], v[166:169]
	v_mfma_f32_16x16x32_bf16 v[40:43], v[68:71], v[226:229], v[170:173]
	v_mfma_f32_16x16x32_bf16 v[36:39], v[76:79], v[226:229], v[174:177]
	v_mfma_f32_16x16x32_bf16 v[32:35], v[72:75], v[226:229], v[4:7]
	v_mfma_f32_16x16x32_bf16 v[28:31], v[64:67], v[230:233], v[178:181]
	v_mfma_f32_16x16x32_bf16 v[24:27], v[68:71], v[230:233], v[182:185]
	v_mfma_f32_16x16x32_bf16 v[20:23], v[76:79], v[230:233], v[186:189]
	v_mfma_f32_16x16x32_bf16 v[16:19], v[72:75], v[230:233], v[8:11]
	v_mfma_f32_16x16x32_bf16 v[12:15], v[64:67], v[234:237], v[204:207]
	v_mfma_f32_16x16x32_bf16 v[8:11], v[68:71], v[234:237], v[210:213]
	v_mfma_f32_16x16x32_bf16 v[4:7], v[76:79], v[234:237], v[214:217]
	v_mfma_f32_16x16x32_bf16 v[0:3], v[72:75], v[234:237], v[222:225]
	s_setprio 0
	v_lshlrev_b32_e32 v160, 8, v160
	v_lshlrev_b32_e32 v162, 4, v200
	v_lshlrev_b32_e32 v164, 4, v201
	v_lshlrev_b32_e32 v167, 4, v221
	v_and_or_b32 v160, v160, s90, v191
	v_lshlrev_b32_e32 v166, 11, v161
	s_add_u32 s4, s31, s38
	v_and_or_b32 v162, v162, s90, v191
	v_and_or_b32 v164, v164, s90, v191
	v_and_or_b32 v167, v167, s90, v191
	v_or3_b32 v168, v160, v166, v190
	v_mov_b32_e32 v169, v193
	s_addc_u32 s5, s46, s39
	v_or3_b32 v170, v162, v166, v190
	v_mov_b32_e32 v171, v193
	v_or3_b32 v172, v164, v166, v190
	v_mov_b32_e32 v173, v193
	v_or3_b32 v174, v167, v166, v190
	v_mov_b32_e32 v175, v193
	s_waitcnt lgkmcnt(0)
	v_writelane_b32 v255, s52, 12
	v_writelane_b32 v255, s53, 13
	v_writelane_b32 v255, s64, 14
	v_writelane_b32 v255, s65, 15
	v_writelane_b32 v255, s30, 16
	s_mov_b64 s[64:65], s[4:5]
	v_readlane_b32 s4, v254, 18
	s_waitcnt vmcnt(0)
	s_add_u32 s4, s4, s40
	v_readlane_b32 s5, v254, 19
	s_addc_u32 s5, s5, s41
	s_waitcnt vmcnt(0)
	s_mov_b64 s[52:53], s[4:5]
	s_mov_b64 s[4:5], 0
	v_lshrrev_b32_e32 v164, 6, v252
	v_lshlrev_b32_e32 v164, 10, v164
	s_nop 0
	v_readfirstlane_b32 s30, v164
	v_and_b32_e32 v165, 63, v252
	v_lshlrev_b32_e32 v165, 4, v165
	s_barrier
	s_and_b32 s37, s35, 0x10000
	v_add_u32_e32 v221, s37, v218
	v_or_b32_e32 v226, s37, v219
	s_xor_b32 s37, s37, 0x10000
	s_add_u32 s37, s37, s30
.LBB0_111:
	ds_read_b128 v[176:179], v221
	ds_read_b128 v[180:183], v221 offset:2048
	ds_read_b128 v[184:187], v221 offset:4096
	ds_read_b128 v[188:191], v221 offset:6144
	s_add_u32 m0, s37, 0x8000
	ds_read_b128 v[204:207], v226 offset:32768
	global_load_lds_dwordx4 v168, s[64:65]
	s_add_u32 m0, s37, 0xa000
	ds_read_b128 v[210:213], v226 offset:34816
	global_load_lds_dwordx4 v170, s[64:65]
	s_add_u32 m0, s37, 0xc000
	ds_read_b128 v[214:217], v226 offset:36864
	global_load_lds_dwordx4 v172, s[64:65]
	s_add_u32 m0, s37, 0xe000
	ds_read_b128 v[222:225], v226 offset:38912
	global_load_lds_dwordx4 v174, s[64:65]
	s_setprio 1
	v_mfma_f32_16x16x32_bf16 v[128:131], v[64:67], v[156:159], v[128:131]
	v_mfma_f32_16x16x32_bf16 v[124:127], v[68:71], v[156:159], v[124:127]
	v_mfma_f32_16x16x32_bf16 v[120:123], v[76:79], v[156:159], v[120:123]
	v_mfma_f32_16x16x32_bf16 v[116:119], v[72:75], v[156:159], v[116:119]
	v_mfma_f32_16x16x32_bf16 v[112:115], v[64:67], v[152:155], v[112:115]
	v_mfma_f32_16x16x32_bf16 v[108:111], v[68:71], v[152:155], v[108:111]
	v_mfma_f32_16x16x32_bf16 v[104:107], v[76:79], v[152:155], v[104:107]
	v_mfma_f32_16x16x32_bf16 v[100:103], v[72:75], v[152:155], v[100:103]
	v_mfma_f32_16x16x32_bf16 v[96:99], v[64:67], v[148:151], v[96:99]
	v_mfma_f32_16x16x32_bf16 v[92:95], v[68:71], v[148:151], v[92:95]
	v_mfma_f32_16x16x32_bf16 v[88:91], v[76:79], v[148:151], v[88:91]
	v_mfma_f32_16x16x32_bf16 v[84:87], v[72:75], v[148:151], v[84:87]
	v_mfma_f32_16x16x32_bf16 v[132:135], v[64:67], v[144:147], v[132:135]
	v_mfma_f32_16x16x32_bf16 v[136:139], v[68:71], v[144:147], v[136:139]
	v_mfma_f32_16x16x32_bf16 v[140:143], v[76:79], v[144:147], v[140:143]
	v_mfma_f32_16x16x32_bf16 v[80:83], v[72:75], v[144:147], v[80:83]
	s_setprio 0
	s_add_u32 m0, s37, 0x0
	s_nop 0
	global_load_lds_dwordx4 v168, s[52:53]
	s_add_u32 m0, s37, 0x2000
	s_nop 0
	global_load_lds_dwordx4 v170, s[52:53]
	s_add_u32 m0, s37, 0x4000
	s_nop 0
	global_load_lds_dwordx4 v172, s[52:53]
	s_add_u32 m0, s37, 0x6000
	s_nop 0
	global_load_lds_dwordx4 v174, s[52:53]
	ds_read_b128 v[144:147], v221 offset:8192
	ds_read_b128 v[148:151], v221 offset:10240
	ds_read_b128 v[152:155], v221 offset:12288
	ds_read_b128 v[156:159], v221 offset:14336
	s_setprio 1
	s_waitcnt lgkmcnt(4)
; #define WAIT_V0() asm volatile("s_waitcnt vmcnt(0)" ::: "memory")
; #define G_STAGE_A(Ap, buf, kt) do { const char* ab_ = (const char*)(Ap) + (size_t)(kt) * 128; \
;       _Pragma("unroll") for (int i = 0; i < 4; ++i) \
;         __builtin_amdgcn_global_load_lds((const unsigned*)(ab_ + soff[i]), (LDSP unsigned*)(G_SA(buf) + wid * 1024 + i * 8192), 16, 0, 0); } while (0)
; #define G_STAGE_B(Bp, buf, kt) do { const char* bb_ = (const char*)(Bp) + (size_t)(kt) * 128; \
;       _Pragma("unroll") for (int i = 0; i < 4; ++i) \
;         __builtin_amdgcn_global_load_lds((const unsigned*)(bb_ + soff[i]), (LDSP unsigned*)(G_SB(buf) + wid * 1024 + i * 8192), 16, 0, 0); } while (0)
; #define G_RDA(AF, buf, ks, mh) do { _Pragma("unroll") for (int m = 0; m < 4; ++m) AF[m] = *(const LDSP bf16x8*)(G_SA(buf) + aoff + ((mh) * 4 + m) * 2048 + (ks) * 1024); } while (0)
; #define G_RDB(BF, buf, ks) do { _Pragma("unroll") for (int n = 0; n < 4; ++n) BF[n] = *(const LDSP bf16x8*)(G_SB(buf) + boff + n * 2048 + (ks) * 1024); } while (0)
; #define G_MMA(AF, BF, mh) do { __builtin_amdgcn_s_setprio(1); \
;             _Pragma("unroll") for (int m = 0; m < 4; ++m) _Pragma("unroll") for (int n = 0; n < 4; ++n) \
;                 acc[(mh) * 4 + m][n] = __builtin_amdgcn_mfma_f32_16x16x32_bf16(BF[n], AF[m], acc[(mh) * 4 + m][n], 0, 0, 0); \
;             __builtin_amdgcn_s_setprio(0); } while (0)
; template <int EK>
; DI void gemm_stream(const Params& p, int l, const bf16_t* __restrict__ A, const bf16_t* __restrict__ Bt, int M, int N, int K, ldsp_t shm) {
;     ...
;         for (int t = 0; t < nt; ++t) {
;             const int cur = t & 1;
;             G_RDA(Aa, cur, 0, 0); G_RDB(Bk0, cur, 0);
;             if (t + 1 < nt) G_STAGE_B(Bb, cur ^ 1, t + 1);
;             else if (has_next) G_STAGE_B(Bb2, cur ^ 1, 0);
;             G_SB0();
;             if (t > 0) G_MMA(Ab_, Bk1, 1);
;             G_SB0();
;             if (t + 1 < nt) G_STAGE_A(Ab, cur ^ 1, t + 1);
;             else if (has_next) G_STAGE_A(Ab2, cur ^ 1, 0);
;             G_RDA(Ab_, cur, 0, 1);
;             G_MMA(Aa, Bk0, 0); G_SB0();
;             G_RDA(Aa, cur, 1, 0); G_RDB(Bk1, cur, 1);
;             G_MMA(Ab_, Bk0, 1); G_SB0();
;             G_RDA(Ab_, cur, 1, 1);
;             G_MMA(Aa, Bk1, 0); G_SB0();
;             asm volatile("s_waitcnt lgkmcnt(0)" ::: "memory");
;             WAIT_V0(); __syncthreads();
;         }
	v_mfma_f32_16x16x32_bf16 v[60:63], v[204:207], v[176:179], v[60:63]
	v_mfma_f32_16x16x32_bf16 v[56:59], v[210:213], v[176:179], v[56:59]
	v_mfma_f32_16x16x32_bf16 v[52:55], v[214:217], v[176:179], v[52:55]
	v_mfma_f32_16x16x32_bf16 v[48:51], v[222:225], v[176:179], v[48:51]
	v_mfma_f32_16x16x32_bf16 v[44:47], v[204:207], v[180:183], v[44:47]
	v_mfma_f32_16x16x32_bf16 v[40:43], v[210:213], v[180:183], v[40:43]
	v_mfma_f32_16x16x32_bf16 v[36:39], v[214:217], v[180:183], v[36:39]
	v_mfma_f32_16x16x32_bf16 v[32:35], v[222:225], v[180:183], v[32:35]
	v_mfma_f32_16x16x32_bf16 v[28:31], v[204:207], v[184:187], v[28:31]
	v_mfma_f32_16x16x32_bf16 v[24:27], v[210:213], v[184:187], v[24:27]
	v_mfma_f32_16x16x32_bf16 v[20:23], v[214:217], v[184:187], v[20:23]
	v_mfma_f32_16x16x32_bf16 v[16:19], v[222:225], v[184:187], v[16:19]
	v_mfma_f32_16x16x32_bf16 v[12:15], v[204:207], v[188:191], v[12:15]
	v_mfma_f32_16x16x32_bf16 v[8:11], v[210:213], v[188:191], v[8:11]
	v_mfma_f32_16x16x32_bf16 v[4:7], v[214:217], v[188:191], v[4:7]
	v_mfma_f32_16x16x32_bf16 v[0:3], v[222:225], v[188:191], v[0:3]
	s_setprio 0
	ds_read_b128 v[176:179], v221 offset:1024
	ds_read_b128 v[180:183], v221 offset:3072
	ds_read_b128 v[184:187], v221 offset:5120
	ds_read_b128 v[188:191], v221 offset:7168
	ds_read_b128 v[64:67], v226 offset:33792
	ds_read_b128 v[68:71], v226 offset:35840
	ds_read_b128 v[76:79], v226 offset:37888
	ds_read_b128 v[72:75], v226 offset:39936
	s_setprio 1
	s_waitcnt lgkmcnt(8)
	v_mfma_f32_16x16x32_bf16 v[128:131], v[204:207], v[144:147], v[128:131]
	v_mfma_f32_16x16x32_bf16 v[124:127], v[210:213], v[144:147], v[124:127]
	v_mfma_f32_16x16x32_bf16 v[120:123], v[214:217], v[144:147], v[120:123]
	v_mfma_f32_16x16x32_bf16 v[116:119], v[222:225], v[144:147], v[116:119]
	v_mfma_f32_16x16x32_bf16 v[112:115], v[204:207], v[148:151], v[112:115]
	v_mfma_f32_16x16x32_bf16 v[108:111], v[210:213], v[148:151], v[108:111]
	v_mfma_f32_16x16x32_bf16 v[104:107], v[214:217], v[148:151], v[104:107]
	v_mfma_f32_16x16x32_bf16 v[100:103], v[222:225], v[148:151], v[100:103]
	v_mfma_f32_16x16x32_bf16 v[96:99], v[204:207], v[152:155], v[96:99]
	v_mfma_f32_16x16x32_bf16 v[92:95], v[210:213], v[152:155], v[92:95]
	v_mfma_f32_16x16x32_bf16 v[88:91], v[214:217], v[152:155], v[88:91]
	v_mfma_f32_16x16x32_bf16 v[84:87], v[222:225], v[152:155], v[84:87]
	v_mfma_f32_16x16x32_bf16 v[132:135], v[204:207], v[156:159], v[132:135]
	v_mfma_f32_16x16x32_bf16 v[136:139], v[210:213], v[156:159], v[136:139]
	v_mfma_f32_16x16x32_bf16 v[140:143], v[214:217], v[156:159], v[140:143]
	v_mfma_f32_16x16x32_bf16 v[80:83], v[222:225], v[156:159], v[80:83]
	s_setprio 0
	ds_read_b128 v[156:159], v221 offset:9216
	ds_read_b128 v[152:155], v221 offset:11264
	ds_read_b128 v[148:151], v221 offset:13312
	ds_read_b128 v[144:147], v221 offset:15360
	s_setprio 1
	s_waitcnt lgkmcnt(4)
	v_mfma_f32_16x16x32_bf16 v[60:63], v[64:67], v[176:179], v[60:63]
	v_mfma_f32_16x16x32_bf16 v[56:59], v[68:71], v[176:179], v[56:59]
	v_mfma_f32_16x16x32_bf16 v[52:55], v[76:79], v[176:179], v[52:55]
	v_mfma_f32_16x16x32_bf16 v[48:51], v[72:75], v[176:179], v[48:51]
	v_mfma_f32_16x16x32_bf16 v[44:47], v[64:67], v[180:183], v[44:47]
	v_mfma_f32_16x16x32_bf16 v[40:43], v[68:71], v[180:183], v[40:43]
	v_mfma_f32_16x16x32_bf16 v[36:39], v[76:79], v[180:183], v[36:39]
	v_mfma_f32_16x16x32_bf16 v[32:35], v[72:75], v[180:183], v[32:35]
	v_mfma_f32_16x16x32_bf16 v[28:31], v[64:67], v[184:187], v[28:31]
	v_mfma_f32_16x16x32_bf16 v[24:27], v[68:71], v[184:187], v[24:27]
	v_mfma_f32_16x16x32_bf16 v[20:23], v[76:79], v[184:187], v[20:23]
	v_mfma_f32_16x16x32_bf16 v[16:19], v[72:75], v[184:187], v[16:19]
	v_mfma_f32_16x16x32_bf16 v[12:15], v[64:67], v[188:191], v[12:15]
	v_mfma_f32_16x16x32_bf16 v[8:11], v[68:71], v[188:191], v[8:11]
	v_mfma_f32_16x16x32_bf16 v[4:7], v[76:79], v[188:191], v[4:7]
	v_mfma_f32_16x16x32_bf16 v[0:3], v[72:75], v[188:191], v[0:3]
	s_setprio 0
	s_waitcnt lgkmcnt(0)
	s_add_u32 s52, s52, 0x80
	s_addc_u32 s53, s53, 0
	s_add_u32 s64, s64, 0x80
	s_addc_u32 s65, s65, 0
	s_add_u32 s4, s4, 0x80
	s_addc_u32 s5, s5, 0
	s_add_i32 s35, s35, 0x10000
	s_and_b32 s37, s35, 0x10000
	v_add_u32_e32 v221, s37, v218
	v_or_b32_e32 v226, s37, v219
	s_xor_b32 s37, s37, 0x10000
	s_add_u32 s37, s37, s30
	s_cmpk_eq_i32 s4, 0x700
	s_waitcnt vmcnt(0)
	s_barrier
	s_cbranch_scc0 .LBB0_111
	v_readlane_b32 s52, v255, 12
	v_readlane_b32 s53, v255, 13
	v_readlane_b32 s64, v255, 14
	v_readlane_b32 s65, v255, 15
	v_readlane_b32 s30, v255, 16
	v_add_u32_e32 v160, 0x10000, v218
	v_add_u32_e32 v161, 0x10800, v218
	ds_read_b128 v[188:191], v160
	ds_read_b128 v[180:183], v161
	v_add_u32_e32 v160, 0x11000, v218
	v_add_u32_e32 v161, 0x11800, v218
	ds_read_b128 v[184:187], v160
	ds_read_b128 v[176:179], v161
	v_or_b32_e32 v160, 0x18000, v219
	v_add_u32_e32 v164, 0x18800, v219
	v_add_u32_e32 v168, 0x19000, v219
	v_add_u32_e32 v172, 0x19800, v219
	ds_read_b128 v[160:163], v160
	ds_read_b128 v[164:167], v164
	ds_read_b128 v[168:171], v168
	ds_read_b128 v[172:175], v172
	s_ashr_i32 s37, s36, 31
	v_cndmask_b32_e64 v200, 0, 1, s[42:43]
	v_cmp_ne_u32_e64 s[4:5], 1, v200
	s_andn2_b64 vcc, exec, s[42:43]
	s_lshl_b64 s[38:39], s[36:37], 19
	s_cbranch_vccnz .LBB0_114
	s_add_u32 s40, s9, s38
	v_add_u32_e32 v212, 0x8000, v220
	s_addc_u32 s41, s45, s39
	v_add_u32_e32 v215, 0xa000, v220
	v_readfirstlane_b32 s35, v212
	v_lshl_add_u64 v[200:201], s[40:41], 0, v[192:193]
	v_add_u32_e32 v214, 0xc000, v220
	s_mov_b32 m0, s35
	v_readfirstlane_b32 s35, v215
	v_lshl_add_u64 v[204:205], s[40:41], 0, v[194:195]
	v_add_u32_e32 v213, 0xe000, v220
	global_load_lds_dwordx4 v[200:201], off
	s_mov_b32 m0, s35
	v_readfirstlane_b32 s35, v214
	v_lshl_add_u64 v[206:207], s[40:41], 0, v[196:197]
	global_load_lds_dwordx4 v[204:205], off
	s_mov_b32 m0, s35
	v_readfirstlane_b32 s35, v213
	v_lshl_add_u64 v[210:211], s[40:41], 0, v[198:199]
	global_load_lds_dwordx4 v[206:207], off
	s_mov_b32 m0, s35
	s_nop 0
	global_load_lds_dwordx4 v[210:211], off

; #define WAIT_V0() asm volatile("s_waitcnt vmcnt(0)" ::: "memory")
; #define G_LANE_SETUP() \
;     int tid_ = threadIdx.x; \
;     asm volatile("" : "+v"(tid_));    \
;     const int wid = tid_ >> 6, lane = tid_ & 63, wr = wid >> 2, wc = wid & 3, fr = lane & 15, fq = lane >> 4; \
;     unsigned soff[4];        \
;     _Pragma("unroll") for (int i = 0; i < 4; ++i) { int sR, sC; stage_rc2(wid * 1024 + i * 8192 + lane * 16, sR, sC); soff[i] = (unsigned)(sR * K + sC) * 2u; }
; #define G_SB0() __builtin_amdgcn_sched_barrier(0)
; template <int EK>
; DI void gemm_stream(const Params& p, int l, const bf16_t* __restrict__ A, const bf16_t* __restrict__ Bt, int M, int N, int K, ldsp_t shm) {
;     ...
;     const int nt = K / 64;
;     int pm, pn;
;     tile_coords(L, nM, nN, pm, pn);
;     const bf16_t* Ab = A + (size_t)pm * 256 * K;
;     const bf16_t* Bb = Bt + (size_t)pn * 256 * K;
;     { G_LANE_SETUP(); (void)wr; (void)wc; (void)fr; (void)fq; G_STAGE(Ab, Bb, 0, 0); WAIT_V0(); __syncthreads(); }
;     while (true) {
;         G_LANE_SETUP();
;         const int aoff = lds_byte2(wr * 128 + fr, fq * 8), boff = lds_byte2(wc * 64 + fr, fq * 8);
;         f32x4 acc[8][4];
; #pragma unroll
;         for (int m = 0; m < 8; ++m)
; #pragma unroll
;             for (int n = 0; n < 4; ++n) acc[m][n] = (f32x4){0.f, 0.f, 0.f, 0.f};
;         const int Ln = L + gridDim.x;
;         const bool has_next = Ln < nwg;
;         int pm2 = pm, pn2 = pn;
;         if (has_next) tile_coords(Ln, nM, nN, pm2, pn2);
;         const bf16_t* Ab2 = A + (size_t)pm2 * 256 * K;
;         const bf16_t* Bb2 = Bt + (size_t)pn2 * 256 * K;
;         bf16x8 Aa[4], Ab_[4], Bk0[4], Bk1[4];
;     ...
;         for (int t = 0; t < nt; ++t) {
;             const int cur = t & 1;
;             G_RDA(Aa, cur, 0, 0); G_RDB(Bk0, cur, 0);
;             if (t + 1 < nt) G_STAGE_B(Bb, cur ^ 1, t + 1);
;             else if (has_next) G_STAGE_B(Bb2, cur ^ 1, 0);
;             G_SB0();
;             if (t > 0) G_MMA(Ab_, Bk1, 1);
;             G_SB0();
;             if (t + 1 < nt) G_STAGE_A(Ab, cur ^ 1, t + 1);
;             else if (has_next) G_STAGE_A(Ab2, cur ^ 1, 0);
;             G_RDA(Ab_, cur, 0, 1);
;             G_MMA(Aa, Bk0, 0); G_SB0();
;             G_RDA(Aa, cur, 1, 0); G_RDB(Bk1, cur, 1);
;             G_MMA(Ab_, Bk0, 1); G_SB0();
;             G_RDA(Ab_, cur, 1, 1);
;             G_MMA(Aa, Bk1, 0); G_SB0();
.LBB0_131:
	v_lshlrev_b32_e32 v0, 4, v160
	v_and_b32_e32 v1, 32, v160
	v_bfe_u32 v161, v160, 2, 4
	v_and_b32_e32 v190, 64, v160
	v_bitop3_b32 v191, v0, v1, 48 bitop3:0x6c
	v_lshrrev_b32_e32 v2, 3, v160
	s_mov_b32 s6, 0x1ffff0
	v_or_b32_e32 v1, v191, v190
	v_and_or_b32 v2, v2, s6, v161
	v_add_u32_e32 v200, 0x2000, v0
	v_lshl_or_b32 v192, v2, 11, v1
	v_lshrrev_b32_e32 v2, 7, v200
	v_and_or_b32 v2, v2, s6, v161
	v_add_u32_e32 v201, 0x4000, v0
	v_add_u32_e32 v221, 0x6000, v0
	v_and_b32_e32 v220, 0xfffffc00, v0
	v_lshl_or_b32 v194, v2, 11, v1
	v_lshrrev_b32_e32 v2, 7, v201
	v_lshrrev_b32_e32 v0, 7, v221
	v_and_or_b32 v2, v2, s6, v161
	v_and_or_b32 v0, v0, s6, v161
	v_lshl_or_b32 v196, v2, 11, v1
	v_lshl_or_b32 v198, v0, 11, v1
	v_lshlrev_b32_e32 v1, 6, v160
	v_lshlrev_b32_e32 v4, 2, v160
	v_and_b32_e32 v0, 48, v160
	v_and_b32_e32 v2, 0x3c0, v1
	v_and_b32_e32 v4, 32, v4
	v_bitop3_b32 v0, v2, v4, v0 bitop3:0x36
	s_movk_i32 s6, 0xc000
	v_and_or_b32 v218, v1, s6, v0
	s_add_u32 s6, s93, s46
	s_addc_u32 s7, s98, s47
	v_add_u32_e32 v34, 0x18000, v220
	v_lshl_add_u64 v[32:33], s[6:7], 0, v[192:193]
	v_readfirstlane_b32 s41, v34
	v_lshlrev_b32_e32 v3, 7, v160
	v_lshl_add_u64 v[32:33], v[32:33], 0, s[0:1]
	s_mov_b32 m0, s41
	v_mov_b32_e32 v195, v193
	v_add_u32_e32 v34, 0x1a000, v220
	v_and_or_b32 v219, v3, s28, v0
	ds_read_b128 v[0:3], v218
	ds_read_b128 v[4:7], v218 offset:2048
	ds_read_b128 v[8:11], v218 offset:4096
	ds_read_b128 v[12:15], v218 offset:6144
	ds_read_b128 v[16:19], v219 offset:32768
	ds_read_b128 v[20:23], v219 offset:34816
	ds_read_b128 v[24:27], v219 offset:36864
	ds_read_b128 v[28:31], v219 offset:38912
	global_load_lds_dwordx4 v[32:33], off
	v_lshl_add_u64 v[32:33], s[6:7], 0, v[194:195]
	v_readfirstlane_b32 s41, v34
	v_lshl_add_u64 v[32:33], v[32:33], 0, s[0:1]
	s_mov_b32 m0, s41
	v_mov_b32_e32 v197, v193
	v_add_u32_e32 v34, 0x1c000, v220
	global_load_lds_dwordx4 v[32:33], off
	v_lshl_add_u64 v[32:33], s[6:7], 0, v[196:197]
	v_readfirstlane_b32 s41, v34
	v_lshl_add_u64 v[32:33], v[32:33], 0, s[0:1]
	s_mov_b32 m0, s41
	v_mov_b32_e32 v199, v193
	v_add_u32_e32 v34, 0x1e000, v220
	global_load_lds_dwordx4 v[32:33], off
	v_lshl_add_u64 v[32:33], s[6:7], 0, v[198:199]
	v_readfirstlane_b32 s6, v34
	v_lshl_add_u64 v[32:33], v[32:33], 0, s[0:1]
	s_mov_b32 m0, s6
	s_nop 0
	global_load_lds_dwordx4 v[32:33], off
	s_add_u32 s6, s26, s50
	s_addc_u32 s7, s27, s51
	v_add_u32_e32 v34, 0x10000, v220
	v_lshl_add_u64 v[32:33], s[6:7], 0, v[192:193]
	v_readfirstlane_b32 s41, v34
	v_lshl_add_u64 v[32:33], v[32:33], 0, s[0:1]
	s_mov_b32 m0, s41
	v_add_u32_e32 v34, 0x12000, v220
	global_load_lds_dwordx4 v[32:33], off
	v_lshl_add_u64 v[32:33], s[6:7], 0, v[194:195]
	v_readfirstlane_b32 s41, v34
	v_lshl_add_u64 v[32:33], v[32:33], 0, s[0:1]
	s_mov_b32 m0, s41
	v_add_u32_e32 v34, 0x14000, v220
	global_load_lds_dwordx4 v[32:33], off
	v_lshl_add_u64 v[32:33], s[6:7], 0, v[196:197]
	v_readfirstlane_b32 s41, v34
	v_lshl_add_u64 v[32:33], v[32:33], 0, s[0:1]
	s_mov_b32 m0, s41
	v_add_u32_e32 v34, 0x16000, v220
	global_load_lds_dwordx4 v[32:33], off
	v_lshl_add_u64 v[32:33], s[6:7], 0, v[198:199]
	v_readfirstlane_b32 s6, v34
	v_lshl_add_u64 v[32:33], v[32:33], 0, s[0:1]
	s_mov_b32 m0, s6
	s_mov_b32 s41, 0x10000
	global_load_lds_dwordx4 v[32:33], off
	ds_read_b128 v[32:35], v218 offset:8192
	ds_read_b128 v[36:39], v218 offset:10240
	ds_read_b128 v[40:43], v218 offset:12288
	ds_read_b128 v[44:47], v218 offset:14336
	s_setprio 1
	s_waitcnt lgkmcnt(0)
	v_mfma_f32_16x16x32_bf16 v[48:51], v[16:19], v[0:3], 0
	v_mfma_f32_16x16x32_bf16 v[52:55], v[20:23], v[0:3], 0
	v_mfma_f32_16x16x32_bf16 v[56:59], v[24:27], v[0:3], 0
	v_mfma_f32_16x16x32_bf16 v[60:63], v[28:31], v[0:3], 0
	v_mfma_f32_16x16x32_bf16 v[162:165], v[16:19], v[4:7], 0
	v_mfma_f32_16x16x32_bf16 v[166:169], v[20:23], v[4:7], 0
	v_mfma_f32_16x16x32_bf16 v[170:173], v[24:27], v[4:7], 0
	v_mfma_f32_16x16x32_bf16 v[174:177], v[28:31], v[4:7], 0
	v_mfma_f32_16x16x32_bf16 v[178:181], v[16:19], v[8:11], 0
	v_mfma_f32_16x16x32_bf16 v[182:185], v[20:23], v[8:11], 0
	v_mfma_f32_16x16x32_bf16 v[186:189], v[24:27], v[8:11], 0
	v_mfma_f32_16x16x32_bf16 v[204:207], v[28:31], v[8:11], 0
	v_mfma_f32_16x16x32_bf16 v[210:213], v[16:19], v[12:15], 0
	v_mfma_f32_16x16x32_bf16 v[214:217], v[20:23], v[12:15], 0
	v_mfma_f32_16x16x32_bf16 v[222:225], v[24:27], v[12:15], 0
	v_mfma_f32_16x16x32_bf16 v[226:229], v[28:31], v[12:15], 0
	s_setprio 0
	ds_read_b128 v[12:15], v218 offset:1024
	ds_read_b128 v[230:233], v218 offset:3072
	ds_read_b128 v[234:237], v218 offset:5120
	ds_read_b128 v[238:241], v218 offset:7168
	ds_read_b128 v[64:67], v219 offset:33792
	ds_read_b128 v[68:71], v219 offset:35840
	ds_read_b128 v[72:75], v219 offset:37888
	ds_read_b128 v[76:79], v219 offset:39936
	s_setprio 1
	v_mfma_f32_16x16x32_bf16 v[140:143], v[16:19], v[32:35], 0
	v_mfma_f32_16x16x32_bf16 v[136:139], v[20:23], v[32:35], 0
	v_mfma_f32_16x16x32_bf16 v[132:135], v[24:27], v[32:35], 0
	v_mfma_f32_16x16x32_bf16 v[128:131], v[28:31], v[32:35], 0
	v_mfma_f32_16x16x32_bf16 v[124:127], v[16:19], v[36:39], 0
	v_mfma_f32_16x16x32_bf16 v[120:123], v[20:23], v[36:39], 0
	v_mfma_f32_16x16x32_bf16 v[116:119], v[24:27], v[36:39], 0
	v_mfma_f32_16x16x32_bf16 v[112:115], v[28:31], v[36:39], 0
	v_mfma_f32_16x16x32_bf16 v[108:111], v[16:19], v[40:43], 0
	v_mfma_f32_16x16x32_bf16 v[104:107], v[20:23], v[40:43], 0
	v_mfma_f32_16x16x32_bf16 v[100:103], v[24:27], v[40:43], 0
	v_mfma_f32_16x16x32_bf16 v[96:99], v[28:31], v[40:43], 0
	v_mfma_f32_16x16x32_bf16 v[92:95], v[16:19], v[44:47], 0
	v_mfma_f32_16x16x32_bf16 v[88:91], v[20:23], v[44:47], 0
	v_mfma_f32_16x16x32_bf16 v[84:87], v[24:27], v[44:47], 0
	v_mfma_f32_16x16x32_bf16 v[80:83], v[28:31], v[44:47], 0
	s_setprio 0
	ds_read_b128 v[156:159], v218 offset:9216
	ds_read_b128 v[152:155], v218 offset:11264
	ds_read_b128 v[148:151], v218 offset:13312
	ds_read_b128 v[144:147], v218 offset:15360
	s_setprio 1
	s_waitcnt lgkmcnt(0)
; #define WAIT_V0() asm volatile("s_waitcnt vmcnt(0)" ::: "memory")
; #define G_STAGE_A(Ap, buf, kt) do { const char* ab_ = (const char*)(Ap) + (size_t)(kt) * 128; \
;       _Pragma("unroll") for (int i = 0; i < 4; ++i) \
;         __builtin_amdgcn_global_load_lds((const unsigned*)(ab_ + soff[i]), (LDSP unsigned*)(G_SA(buf) + wid * 1024 + i * 8192), 16, 0, 0); } while (0)
; #define G_STAGE_B(Bp, buf, kt) do { const char* bb_ = (const char*)(Bp) + (size_t)(kt) * 128; \
;       _Pragma("unroll") for (int i = 0; i < 4; ++i) \
;         __builtin_amdgcn_global_load_lds((const unsigned*)(bb_ + soff[i]), (LDSP unsigned*)(G_SB(buf) + wid * 1024 + i * 8192), 16, 0, 0); } while (0)
; #define G_RDA(AF, buf, ks, mh) do { _Pragma("unroll") for (int m = 0; m < 4; ++m) AF[m] = *(const LDSP bf16x8*)(G_SA(buf) + aoff + ((mh) * 4 + m) * 2048 + (ks) * 1024); } while (0)
; #define G_RDB(BF, buf, ks) do { _Pragma("unroll") for (int n = 0; n < 4; ++n) BF[n] = *(const LDSP bf16x8*)(G_SB(buf) + boff + n * 2048 + (ks) * 1024); } while (0)
; #define G_MMA(AF, BF, mh) do { __builtin_amdgcn_s_setprio(1); \
;             _Pragma("unroll") for (int m = 0; m < 4; ++m) _Pragma("unroll") for (int n = 0; n < 4; ++n) \
;                 acc[(mh) * 4 + m][n] = __builtin_amdgcn_mfma_f32_16x16x32_bf16(BF[n], AF[m], acc[(mh) * 4 + m][n], 0, 0, 0); \
;             __builtin_amdgcn_s_setprio(0); } while (0)
; template <int EK>
; DI void gemm_stream(const Params& p, int l, const bf16_t* __restrict__ A, const bf16_t* __restrict__ Bt, int M, int N, int K, ldsp_t shm) {
;     ...
;         for (int t = 0; t < nt; ++t) {
;             const int cur = t & 1;
;             G_RDA(Aa, cur, 0, 0); G_RDB(Bk0, cur, 0);
;             if (t + 1 < nt) G_STAGE_B(Bb, cur ^ 1, t + 1);
;             else if (has_next) G_STAGE_B(Bb2, cur ^ 1, 0);
;             G_SB0();
;             if (t > 0) G_MMA(Ab_, Bk1, 1);
;             G_SB0();
;             if (t + 1 < nt) G_STAGE_A(Ab, cur ^ 1, t + 1);
;             else if (has_next) G_STAGE_A(Ab2, cur ^ 1, 0);
;             G_RDA(Ab_, cur, 0, 1);
;             G_MMA(Aa, Bk0, 0); G_SB0();
;             G_RDA(Aa, cur, 1, 0); G_RDB(Bk1, cur, 1);
;             G_MMA(Ab_, Bk0, 1); G_SB0();
;             G_RDA(Ab_, cur, 1, 1);
;             G_MMA(Aa, Bk1, 0); G_SB0();
;             asm volatile("s_waitcnt lgkmcnt(0)" ::: "memory");
;             WAIT_V0(); __syncthreads();
;         }
	v_mfma_f32_16x16x32_bf16 v[0:3], v[64:67], v[12:15], v[48:51]
	v_mfma_f32_16x16x32_bf16 v[4:7], v[68:71], v[12:15], v[52:55]
	v_mfma_f32_16x16x32_bf16 v[8:11], v[72:75], v[12:15], v[56:59]
	v_mfma_f32_16x16x32_bf16 v[12:15], v[76:79], v[12:15], v[60:63]
	v_mfma_f32_16x16x32_bf16 v[16:19], v[64:67], v[230:233], v[162:165]
	v_mfma_f32_16x16x32_bf16 v[20:23], v[68:71], v[230:233], v[166:169]
	v_mfma_f32_16x16x32_bf16 v[24:27], v[72:75], v[230:233], v[170:173]
	v_mfma_f32_16x16x32_bf16 v[28:31], v[76:79], v[230:233], v[174:177]
	v_mfma_f32_16x16x32_bf16 v[32:35], v[64:67], v[234:237], v[178:181]
	v_mfma_f32_16x16x32_bf16 v[36:39], v[68:71], v[234:237], v[182:185]
	v_mfma_f32_16x16x32_bf16 v[40:43], v[72:75], v[234:237], v[186:189]
	v_mfma_f32_16x16x32_bf16 v[44:47], v[76:79], v[234:237], v[204:207]
	v_mfma_f32_16x16x32_bf16 v[48:51], v[64:67], v[238:241], v[210:213]
	v_mfma_f32_16x16x32_bf16 v[52:55], v[68:71], v[238:241], v[214:217]
	v_mfma_f32_16x16x32_bf16 v[56:59], v[72:75], v[238:241], v[222:225]
	v_mfma_f32_16x16x32_bf16 v[60:63], v[76:79], v[238:241], v[226:229]
	s_setprio 0
	v_lshlrev_b32_e32 v160, 8, v160
	v_lshlrev_b32_e32 v162, 4, v200
	v_lshlrev_b32_e32 v164, 4, v201
	v_lshlrev_b32_e32 v167, 4, v221
	v_and_or_b32 v160, v160, s90, v191
	v_lshlrev_b32_e32 v166, 11, v161
	s_add_u32 s6, s84, s46
	v_and_or_b32 v162, v162, s90, v191
	v_and_or_b32 v164, v164, s90, v191
	v_and_or_b32 v167, v167, s90, v191
	s_waitcnt lgkmcnt(0)
	v_or3_b32 v168, v160, v166, v190
	v_mov_b32_e32 v169, v193
	s_addc_u32 s7, s85, s47
	v_or3_b32 v170, v162, v166, v190
	v_mov_b32_e32 v171, v193
	v_or3_b32 v172, v164, v166, v190
	v_mov_b32_e32 v173, v193
	v_or3_b32 v174, v167, v166, v190
	v_mov_b32_e32 v175, v193
	s_waitcnt vmcnt(0)
	v_writelane_b32 v255, s52, 12
	v_writelane_b32 v255, s53, 13
	v_writelane_b32 v255, s64, 14
	v_writelane_b32 v255, s65, 15
	v_writelane_b32 v255, s30, 16
	s_mov_b64 s[64:65], s[6:7]
	s_add_u32 s6, s24, s50
	s_addc_u32 s7, s25, s51
	s_mov_b64 s[52:53], s[6:7]
	s_mov_b64 s[6:7], 0
	s_waitcnt vmcnt(0)
	v_lshrrev_b32_e32 v164, 6, v252
	v_lshlrev_b32_e32 v164, 10, v164
	s_nop 0
	v_readfirstlane_b32 s30, v164
	v_and_b32_e32 v165, 63, v252
	v_lshlrev_b32_e32 v165, 4, v165
	s_barrier
	s_and_b32 s43, s41, 0x10000
	v_add_u32_e32 v221, s43, v218
	v_or_b32_e32 v226, s43, v219
	s_xor_b32 s43, s43, 0x10000
	s_add_u32 s43, s43, s30
.LBB0_132:
	ds_read_b128 v[176:179], v221
	ds_read_b128 v[180:183], v221 offset:2048
	ds_read_b128 v[184:187], v221 offset:4096
	ds_read_b128 v[188:191], v221 offset:6144
	s_add_u32 m0, s43, 0x8000
	ds_read_b128 v[204:207], v226 offset:32768
	global_load_lds_dwordx4 v168, s[64:65]
	s_add_u32 m0, s43, 0xa000
	ds_read_b128 v[210:213], v226 offset:34816
	global_load_lds_dwordx4 v170, s[64:65]
	s_add_u32 m0, s43, 0xc000
	ds_read_b128 v[214:217], v226 offset:36864
	global_load_lds_dwordx4 v172, s[64:65]
	s_add_u32 m0, s43, 0xe000
	ds_read_b128 v[222:225], v226 offset:38912
	global_load_lds_dwordx4 v174, s[64:65]
	s_setprio 1
	v_mfma_f32_16x16x32_bf16 v[140:143], v[64:67], v[156:159], v[140:143]
	v_mfma_f32_16x16x32_bf16 v[136:139], v[68:71], v[156:159], v[136:139]
	v_mfma_f32_16x16x32_bf16 v[132:135], v[72:75], v[156:159], v[132:135]
	v_mfma_f32_16x16x32_bf16 v[128:131], v[76:79], v[156:159], v[128:131]
	v_mfma_f32_16x16x32_bf16 v[124:127], v[64:67], v[152:155], v[124:127]
	v_mfma_f32_16x16x32_bf16 v[120:123], v[68:71], v[152:155], v[120:123]
	v_mfma_f32_16x16x32_bf16 v[116:119], v[72:75], v[152:155], v[116:119]
	v_mfma_f32_16x16x32_bf16 v[112:115], v[76:79], v[152:155], v[112:115]
	v_mfma_f32_16x16x32_bf16 v[108:111], v[64:67], v[148:151], v[108:111]
	v_mfma_f32_16x16x32_bf16 v[104:107], v[68:71], v[148:151], v[104:107]
	v_mfma_f32_16x16x32_bf16 v[100:103], v[72:75], v[148:151], v[100:103]
	v_mfma_f32_16x16x32_bf16 v[96:99], v[76:79], v[148:151], v[96:99]
	v_mfma_f32_16x16x32_bf16 v[92:95], v[64:67], v[144:147], v[92:95]
	v_mfma_f32_16x16x32_bf16 v[88:91], v[68:71], v[144:147], v[88:91]
	v_mfma_f32_16x16x32_bf16 v[84:87], v[72:75], v[144:147], v[84:87]
	v_mfma_f32_16x16x32_bf16 v[80:83], v[76:79], v[144:147], v[80:83]
	s_setprio 0
	s_add_u32 m0, s43, 0x0
	s_nop 0
	global_load_lds_dwordx4 v168, s[52:53]
	s_add_u32 m0, s43, 0x2000
	s_nop 0
	global_load_lds_dwordx4 v170, s[52:53]
	s_add_u32 m0, s43, 0x4000
	s_nop 0
	global_load_lds_dwordx4 v172, s[52:53]
	s_add_u32 m0, s43, 0x6000
	s_nop 0
	global_load_lds_dwordx4 v174, s[52:53]
	ds_read_b128 v[144:147], v221 offset:8192
	ds_read_b128 v[148:151], v221 offset:10240
	ds_read_b128 v[152:155], v221 offset:12288
	ds_read_b128 v[156:159], v221 offset:14336
	s_setprio 1
	s_waitcnt lgkmcnt(4)
; #define WAIT_V0() asm volatile("s_waitcnt vmcnt(0)" ::: "memory")
; #define G_STAGE_A(Ap, buf, kt) do { const char* ab_ = (const char*)(Ap) + (size_t)(kt) * 128; \
;       _Pragma("unroll") for (int i = 0; i < 4; ++i) \
;         __builtin_amdgcn_global_load_lds((const unsigned*)(ab_ + soff[i]), (LDSP unsigned*)(G_SA(buf) + wid * 1024 + i * 8192), 16, 0, 0); } while (0)
; #define G_STAGE_B(Bp, buf, kt) do { const char* bb_ = (const char*)(Bp) + (size_t)(kt) * 128; \
;       _Pragma("unroll") for (int i = 0; i < 4; ++i) \
;         __builtin_amdgcn_global_load_lds((const unsigned*)(bb_ + soff[i]), (LDSP unsigned*)(G_SB(buf) + wid * 1024 + i * 8192), 16, 0, 0); } while (0)
; #define G_RDA(AF, buf, ks, mh) do { _Pragma("unroll") for (int m = 0; m < 4; ++m) AF[m] = *(const LDSP bf16x8*)(G_SA(buf) + aoff + ((mh) * 4 + m) * 2048 + (ks) * 1024); } while (0)
; #define G_RDB(BF, buf, ks) do { _Pragma("unroll") for (int n = 0; n < 4; ++n) BF[n] = *(const LDSP bf16x8*)(G_SB(buf) + boff + n * 2048 + (ks) * 1024); } while (0)
; #define G_MMA(AF, BF, mh) do { __builtin_amdgcn_s_setprio(1); \
;             _Pragma("unroll") for (int m = 0; m < 4; ++m) _Pragma("unroll") for (int n = 0; n < 4; ++n) \
;                 acc[(mh) * 4 + m][n] = __builtin_amdgcn_mfma_f32_16x16x32_bf16(BF[n], AF[m], acc[(mh) * 4 + m][n], 0, 0, 0); \
;             __builtin_amdgcn_s_setprio(0); } while (0)
; template <int EK>
; DI void gemm_stream(const Params& p, int l, const bf16_t* __restrict__ A, const bf16_t* __restrict__ Bt, int M, int N, int K, ldsp_t shm) {
;     ...
;         for (int t = 0; t < nt; ++t) {
;             const int cur = t & 1;
;             G_RDA(Aa, cur, 0, 0); G_RDB(Bk0, cur, 0);
;             if (t + 1 < nt) G_STAGE_B(Bb, cur ^ 1, t + 1);
;             else if (has_next) G_STAGE_B(Bb2, cur ^ 1, 0);
;             G_SB0();
;             if (t > 0) G_MMA(Ab_, Bk1, 1);
;             G_SB0();
;             if (t + 1 < nt) G_STAGE_A(Ab, cur ^ 1, t + 1);
;             else if (has_next) G_STAGE_A(Ab2, cur ^ 1, 0);
;             G_RDA(Ab_, cur, 0, 1);
;             G_MMA(Aa, Bk0, 0); G_SB0();
;             G_RDA(Aa, cur, 1, 0); G_RDB(Bk1, cur, 1);
;             G_MMA(Ab_, Bk0, 1); G_SB0();
;             G_RDA(Ab_, cur, 1, 1);
;             G_MMA(Aa, Bk1, 0); G_SB0();
;             asm volatile("s_waitcnt lgkmcnt(0)" ::: "memory");
;             WAIT_V0(); __syncthreads();
;         }
	v_mfma_f32_16x16x32_bf16 v[0:3], v[204:207], v[176:179], v[0:3]
	v_mfma_f32_16x16x32_bf16 v[4:7], v[210:213], v[176:179], v[4:7]
	v_mfma_f32_16x16x32_bf16 v[8:11], v[214:217], v[176:179], v[8:11]
	v_mfma_f32_16x16x32_bf16 v[12:15], v[222:225], v[176:179], v[12:15]
	v_mfma_f32_16x16x32_bf16 v[16:19], v[204:207], v[180:183], v[16:19]
	v_mfma_f32_16x16x32_bf16 v[20:23], v[210:213], v[180:183], v[20:23]
	v_mfma_f32_16x16x32_bf16 v[24:27], v[214:217], v[180:183], v[24:27]
	v_mfma_f32_16x16x32_bf16 v[28:31], v[222:225], v[180:183], v[28:31]
	v_mfma_f32_16x16x32_bf16 v[32:35], v[204:207], v[184:187], v[32:35]
	v_mfma_f32_16x16x32_bf16 v[36:39], v[210:213], v[184:187], v[36:39]
	v_mfma_f32_16x16x32_bf16 v[40:43], v[214:217], v[184:187], v[40:43]
	v_mfma_f32_16x16x32_bf16 v[44:47], v[222:225], v[184:187], v[44:47]
	v_mfma_f32_16x16x32_bf16 v[48:51], v[204:207], v[188:191], v[48:51]
	v_mfma_f32_16x16x32_bf16 v[52:55], v[210:213], v[188:191], v[52:55]
	v_mfma_f32_16x16x32_bf16 v[56:59], v[214:217], v[188:191], v[56:59]
	v_mfma_f32_16x16x32_bf16 v[60:63], v[222:225], v[188:191], v[60:63]
	s_setprio 0
	ds_read_b128 v[176:179], v221 offset:1024
	ds_read_b128 v[180:183], v221 offset:3072
	ds_read_b128 v[184:187], v221 offset:5120
	ds_read_b128 v[188:191], v221 offset:7168
	ds_read_b128 v[64:67], v226 offset:33792
	ds_read_b128 v[68:71], v226 offset:35840
	ds_read_b128 v[72:75], v226 offset:37888
	ds_read_b128 v[76:79], v226 offset:39936
	s_setprio 1
	s_waitcnt lgkmcnt(8)
	v_mfma_f32_16x16x32_bf16 v[140:143], v[204:207], v[144:147], v[140:143]
	v_mfma_f32_16x16x32_bf16 v[136:139], v[210:213], v[144:147], v[136:139]
	v_mfma_f32_16x16x32_bf16 v[132:135], v[214:217], v[144:147], v[132:135]
	v_mfma_f32_16x16x32_bf16 v[128:131], v[222:225], v[144:147], v[128:131]
	v_mfma_f32_16x16x32_bf16 v[124:127], v[204:207], v[148:151], v[124:127]
	v_mfma_f32_16x16x32_bf16 v[120:123], v[210:213], v[148:151], v[120:123]
	v_mfma_f32_16x16x32_bf16 v[116:119], v[214:217], v[148:151], v[116:119]
	v_mfma_f32_16x16x32_bf16 v[112:115], v[222:225], v[148:151], v[112:115]
	v_mfma_f32_16x16x32_bf16 v[108:111], v[204:207], v[152:155], v[108:111]
	v_mfma_f32_16x16x32_bf16 v[104:107], v[210:213], v[152:155], v[104:107]
	v_mfma_f32_16x16x32_bf16 v[100:103], v[214:217], v[152:155], v[100:103]
	v_mfma_f32_16x16x32_bf16 v[96:99], v[222:225], v[152:155], v[96:99]
	v_mfma_f32_16x16x32_bf16 v[92:95], v[204:207], v[156:159], v[92:95]
	v_mfma_f32_16x16x32_bf16 v[88:91], v[210:213], v[156:159], v[88:91]
	v_mfma_f32_16x16x32_bf16 v[84:87], v[214:217], v[156:159], v[84:87]
	v_mfma_f32_16x16x32_bf16 v[80:83], v[222:225], v[156:159], v[80:83]
	s_setprio 0
	ds_read_b128 v[156:159], v221 offset:9216
	ds_read_b128 v[152:155], v221 offset:11264
	ds_read_b128 v[148:151], v221 offset:13312
	ds_read_b128 v[144:147], v221 offset:15360
	s_setprio 1
	s_waitcnt lgkmcnt(4)
	v_mfma_f32_16x16x32_bf16 v[0:3], v[64:67], v[176:179], v[0:3]
	v_mfma_f32_16x16x32_bf16 v[4:7], v[68:71], v[176:179], v[4:7]
	v_mfma_f32_16x16x32_bf16 v[8:11], v[72:75], v[176:179], v[8:11]
	v_mfma_f32_16x16x32_bf16 v[12:15], v[76:79], v[176:179], v[12:15]
	v_mfma_f32_16x16x32_bf16 v[16:19], v[64:67], v[180:183], v[16:19]
	v_mfma_f32_16x16x32_bf16 v[20:23], v[68:71], v[180:183], v[20:23]
	v_mfma_f32_16x16x32_bf16 v[24:27], v[72:75], v[180:183], v[24:27]
	v_mfma_f32_16x16x32_bf16 v[28:31], v[76:79], v[180:183], v[28:31]
	v_mfma_f32_16x16x32_bf16 v[32:35], v[64:67], v[184:187], v[32:35]
	v_mfma_f32_16x16x32_bf16 v[36:39], v[68:71], v[184:187], v[36:39]
	v_mfma_f32_16x16x32_bf16 v[40:43], v[72:75], v[184:187], v[40:43]
	v_mfma_f32_16x16x32_bf16 v[44:47], v[76:79], v[184:187], v[44:47]
	v_mfma_f32_16x16x32_bf16 v[48:51], v[64:67], v[188:191], v[48:51]
	v_mfma_f32_16x16x32_bf16 v[52:55], v[68:71], v[188:191], v[52:55]
	v_mfma_f32_16x16x32_bf16 v[56:59], v[72:75], v[188:191], v[56:59]
	v_mfma_f32_16x16x32_bf16 v[60:63], v[76:79], v[188:191], v[60:63]
	s_setprio 0
	s_waitcnt lgkmcnt(0)
	s_add_u32 s52, s52, 0x80
	s_addc_u32 s53, s53, 0
	s_add_u32 s64, s64, 0x80
	s_addc_u32 s65, s65, 0
	s_add_u32 s6, s6, 0x80
	s_addc_u32 s7, s7, 0
	s_add_i32 s41, s41, 0x10000
	s_and_b32 s43, s41, 0x10000
	v_add_u32_e32 v221, s43, v218
	v_or_b32_e32 v226, s43, v219
	s_xor_b32 s43, s43, 0x10000
	s_add_u32 s43, s43, s30
	s_cmpk_eq_i32 s6, 0x700
	s_waitcnt vmcnt(0)
	s_barrier
	s_cbranch_scc0 .LBB0_132
	v_readlane_b32 s52, v255, 12
	v_readlane_b32 s53, v255, 13
	v_readlane_b32 s64, v255, 14
	v_readlane_b32 s65, v255, 15
	v_readlane_b32 s30, v255, 16
	v_add_u32_e32 v160, 0x10000, v218
	v_add_u32_e32 v161, 0x10800, v218
	ds_read_b128 v[188:191], v160
	ds_read_b128 v[180:183], v161
	v_add_u32_e32 v160, 0x11000, v218
	v_add_u32_e32 v161, 0x11800, v218
	ds_read_b128 v[184:187], v160
	ds_read_b128 v[176:179], v161
	v_or_b32_e32 v160, 0x18000, v219
	v_add_u32_e32 v164, 0x18800, v219
	v_add_u32_e32 v168, 0x19000, v219
	v_add_u32_e32 v172, 0x19800, v219
	ds_read_b128 v[160:163], v160
	ds_read_b128 v[164:167], v164
	ds_read_b128 v[168:171], v168
	ds_read_b128 v[172:175], v172
	s_ashr_i32 s43, s42, 31
	v_cndmask_b32_e64 v200, 0, 1, s[38:39]
	v_cmp_ne_u32_e64 s[6:7], 1, v200
	s_andn2_b64 vcc, exec, s[38:39]
	s_lshl_b64 s[46:47], s[42:43], 19
	s_cbranch_vccnz .LBB0_135
	s_add_u32 s38, s93, s46
	s_addc_u32 s39, s98, s47
	v_add_u32_e32 v212, 0x8000, v220
	v_lshl_add_u64 v[200:201], s[38:39], 0, v[192:193]
	v_lshl_add_u64 v[204:205], s[38:39], 0, v[194:195]
	v_lshl_add_u64 v[206:207], s[38:39], 0, v[196:197]
	v_lshl_add_u64 v[210:211], s[38:39], 0, v[198:199]
	v_add_u32_e32 v215, 0xa000, v220
	v_readfirstlane_b32 s38, v212
	v_add_u32_e32 v214, 0xc000, v220
	s_mov_b32 m0, s38
	v_readfirstlane_b32 s38, v215
	v_add_u32_e32 v213, 0xe000, v220
	global_load_lds_dwordx4 v[200:201], off
	s_mov_b32 m0, s38
	v_readfirstlane_b32 s38, v214
	global_load_lds_dwordx4 v[204:205], off
	s_mov_b32 m0, s38
	v_readfirstlane_b32 s38, v213
	global_load_lds_dwordx4 v[206:207], off
	s_mov_b32 m0, s38
	s_nop 0
	global_load_lds_dwordx4 v[210:211], off

; #define WAIT_V0() asm volatile("s_waitcnt vmcnt(0)" ::: "memory")
; #define G_LANE_SETUP() \
;     int tid_ = threadIdx.x; \
;     asm volatile("" : "+v"(tid_));    \
;     const int wid = tid_ >> 6, lane = tid_ & 63, wr = wid >> 2, wc = wid & 3, fr = lane & 15, fq = lane >> 4; \
;     unsigned soff[4];        \
;     _Pragma("unroll") for (int i = 0; i < 4; ++i) { int sR, sC; stage_rc2(wid * 1024 + i * 8192 + lane * 16, sR, sC); soff[i] = (unsigned)(sR * K + sC) * 2u; }
; #define G_SB0() __builtin_amdgcn_sched_barrier(0)
; template <int EK>
; DI void gemm_stream(const Params& p, int l, const bf16_t* __restrict__ A, const bf16_t* __restrict__ Bt, int M, int N, int K, ldsp_t shm) {
;     ...
;     const int nt = K / 64;
;     int pm, pn;
;     tile_coords(L, nM, nN, pm, pn);
;     const bf16_t* Ab = A + (size_t)pm * 256 * K;
;     const bf16_t* Bb = Bt + (size_t)pn * 256 * K;
;     { G_LANE_SETUP(); (void)wr; (void)wc; (void)fr; (void)fq; G_STAGE(Ab, Bb, 0, 0); WAIT_V0(); __syncthreads(); }
;     while (true) {
;         G_LANE_SETUP();
;         const int aoff = lds_byte2(wr * 128 + fr, fq * 8), boff = lds_byte2(wc * 64 + fr, fq * 8);
;         f32x4 acc[8][4];
; #pragma unroll
;         for (int m = 0; m < 8; ++m)
; #pragma unroll
;             for (int n = 0; n < 4; ++n) acc[m][n] = (f32x4){0.f, 0.f, 0.f, 0.f};
;         const int Ln = L + gridDim.x;
;         const bool has_next = Ln < nwg;
;         int pm2 = pm, pn2 = pn;
;         if (has_next) tile_coords(Ln, nM, nN, pm2, pn2);
;         const bf16_t* Ab2 = A + (size_t)pm2 * 256 * K;
;         const bf16_t* Bb2 = Bt + (size_t)pn2 * 256 * K;
;         bf16x8 Aa[4], Ab_[4], Bk0[4], Bk1[4];
;     ...
;         for (int t = 0; t < nt; ++t) {
;             const int cur = t & 1;
;             G_RDA(Aa, cur, 0, 0); G_RDB(Bk0, cur, 0);
;             if (t + 1 < nt) G_STAGE_B(Bb, cur ^ 1, t + 1);
;             else if (has_next) G_STAGE_B(Bb2, cur ^ 1, 0);
;             G_SB0();
;             if (t > 0) G_MMA(Ab_, Bk1, 1);
;             G_SB0();
;             if (t + 1 < nt) G_STAGE_A(Ab, cur ^ 1, t + 1);
;             else if (has_next) G_STAGE_A(Ab2, cur ^ 1, 0);
;             G_RDA(Ab_, cur, 0, 1);
;             G_MMA(Aa, Bk0, 0); G_SB0();
;             G_RDA(Aa, cur, 1, 0); G_RDB(Bk1, cur, 1);
;             G_MMA(Ab_, Bk0, 1); G_SB0();
;             G_RDA(Ab_, cur, 1, 1);
;             G_MMA(Aa, Bk1, 0); G_SB0();
.LBB0_190:
	v_lshlrev_b32_e32 v0, 4, v160
	v_and_b32_e32 v1, 32, v160
	v_bfe_u32 v161, v160, 2, 4
	v_and_b32_e32 v190, 64, v160
	v_bitop3_b32 v191, v0, v1, 48 bitop3:0x6c
	v_lshrrev_b32_e32 v2, 3, v160
	v_or_b32_e32 v1, v191, v190
	v_and_or_b32 v2, v2, s15, v161
	v_add_u32_e32 v200, 0x2000, v0
	v_lshl_or_b32 v192, v2, 13, v1
	v_lshrrev_b32_e32 v2, 7, v200
	v_and_or_b32 v2, v2, s15, v161
	v_add_u32_e32 v201, 0x4000, v0
	v_add_u32_e32 v221, 0x6000, v0
	v_and_b32_e32 v220, 0xfffffc00, v0
	v_lshl_or_b32 v194, v2, 13, v1
	v_lshrrev_b32_e32 v2, 7, v201
	v_lshrrev_b32_e32 v0, 7, v221
	v_and_or_b32 v2, v2, s15, v161
	v_and_or_b32 v0, v0, s15, v161
	v_lshl_or_b32 v196, v2, 13, v1
	v_lshl_or_b32 v198, v0, 13, v1
	v_lshlrev_b32_e32 v1, 6, v160
	v_lshlrev_b32_e32 v4, 2, v160
	v_and_b32_e32 v0, 48, v160
	v_and_b32_e32 v2, 0x3c0, v1
	v_and_b32_e32 v4, 32, v4
	v_bitop3_b32 v0, v2, v4, v0 bitop3:0x36
	s_movk_i32 s4, 0xc000
	v_and_or_b32 v218, v1, s4, v0
	s_add_u32 s4, s9, s50
	s_addc_u32 s5, s31, s51
	v_add_u32_e32 v34, 0x18000, v220
	v_lshl_add_u64 v[32:33], s[4:5], 0, v[192:193]
	v_readfirstlane_b32 s43, v34
	v_lshlrev_b32_e32 v3, 7, v160
	v_lshl_add_u64 v[32:33], v[32:33], 0, s[0:1]
	s_mov_b32 m0, s43
	v_mov_b32_e32 v195, v193
	v_add_u32_e32 v34, 0x1a000, v220
	v_and_or_b32 v219, v3, s28, v0
	ds_read_b128 v[0:3], v218
	ds_read_b128 v[4:7], v218 offset:2048
	ds_read_b128 v[8:11], v218 offset:4096
	ds_read_b128 v[12:15], v218 offset:6144
	ds_read_b128 v[16:19], v219 offset:32768
	ds_read_b128 v[20:23], v219 offset:34816
	ds_read_b128 v[24:27], v219 offset:36864
	ds_read_b128 v[28:31], v219 offset:38912
	global_load_lds_dwordx4 v[32:33], off
	v_lshl_add_u64 v[32:33], s[4:5], 0, v[194:195]
	v_readfirstlane_b32 s43, v34
	v_lshl_add_u64 v[32:33], v[32:33], 0, s[0:1]
	s_mov_b32 m0, s43
	v_mov_b32_e32 v197, v193
	v_add_u32_e32 v34, 0x1c000, v220
	global_load_lds_dwordx4 v[32:33], off
	v_lshl_add_u64 v[32:33], s[4:5], 0, v[196:197]
	v_readfirstlane_b32 s43, v34
	v_lshl_add_u64 v[32:33], v[32:33], 0, s[0:1]
	s_mov_b32 m0, s43
	v_mov_b32_e32 v199, v193
	v_add_u32_e32 v34, 0x1e000, v220
	global_load_lds_dwordx4 v[32:33], off
	v_lshl_add_u64 v[32:33], s[4:5], 0, v[198:199]
	v_readfirstlane_b32 s4, v34
	v_lshl_add_u64 v[32:33], v[32:33], 0, s[0:1]
	s_mov_b32 m0, s4
	s_nop 0
	global_load_lds_dwordx4 v[32:33], off
	s_add_u32 s4, s12, s6
	s_addc_u32 s5, s13, s7
	v_add_u32_e32 v34, 0x10000, v220
	v_lshl_add_u64 v[32:33], s[4:5], 0, v[192:193]
	v_readfirstlane_b32 s43, v34
	v_lshl_add_u64 v[32:33], v[32:33], 0, s[0:1]
	s_mov_b32 m0, s43
	v_add_u32_e32 v34, 0x12000, v220
	global_load_lds_dwordx4 v[32:33], off
	v_lshl_add_u64 v[32:33], s[4:5], 0, v[194:195]
	v_readfirstlane_b32 s43, v34
	v_lshl_add_u64 v[32:33], v[32:33], 0, s[0:1]
	s_mov_b32 m0, s43
	v_add_u32_e32 v34, 0x14000, v220
	global_load_lds_dwordx4 v[32:33], off
	v_lshl_add_u64 v[32:33], s[4:5], 0, v[196:197]
	v_readfirstlane_b32 s43, v34
	v_lshl_add_u64 v[32:33], v[32:33], 0, s[0:1]
	s_mov_b32 m0, s43
	v_add_u32_e32 v34, 0x16000, v220
	global_load_lds_dwordx4 v[32:33], off
	v_lshl_add_u64 v[32:33], s[4:5], 0, v[198:199]
	v_readfirstlane_b32 s4, v34
	v_lshl_add_u64 v[32:33], v[32:33], 0, s[0:1]
	s_mov_b32 m0, s4
	s_mov_b32 s43, 0x10000
	global_load_lds_dwordx4 v[32:33], off
	ds_read_b128 v[32:35], v218 offset:8192
	ds_read_b128 v[36:39], v218 offset:10240
	ds_read_b128 v[40:43], v218 offset:12288
	ds_read_b128 v[44:47], v218 offset:14336
	s_setprio 1
	s_waitcnt lgkmcnt(0)
	v_mfma_f32_16x16x32_bf16 v[48:51], v[16:19], v[0:3], 0
	v_mfma_f32_16x16x32_bf16 v[52:55], v[20:23], v[0:3], 0
	v_mfma_f32_16x16x32_bf16 v[56:59], v[24:27], v[0:3], 0
	v_mfma_f32_16x16x32_bf16 v[60:63], v[28:31], v[0:3], 0
	v_mfma_f32_16x16x32_bf16 v[162:165], v[16:19], v[4:7], 0
	v_mfma_f32_16x16x32_bf16 v[166:169], v[20:23], v[4:7], 0
	v_mfma_f32_16x16x32_bf16 v[170:173], v[24:27], v[4:7], 0
	v_mfma_f32_16x16x32_bf16 v[174:177], v[28:31], v[4:7], 0
	v_mfma_f32_16x16x32_bf16 v[178:181], v[16:19], v[8:11], 0
	v_mfma_f32_16x16x32_bf16 v[182:185], v[20:23], v[8:11], 0
	v_mfma_f32_16x16x32_bf16 v[186:189], v[24:27], v[8:11], 0
	v_mfma_f32_16x16x32_bf16 v[204:207], v[28:31], v[8:11], 0
	v_mfma_f32_16x16x32_bf16 v[210:213], v[16:19], v[12:15], 0
	v_mfma_f32_16x16x32_bf16 v[214:217], v[20:23], v[12:15], 0
	v_mfma_f32_16x16x32_bf16 v[222:225], v[24:27], v[12:15], 0
	v_mfma_f32_16x16x32_bf16 v[226:229], v[28:31], v[12:15], 0
	s_setprio 0
	ds_read_b128 v[12:15], v218 offset:1024
	ds_read_b128 v[230:233], v218 offset:3072
	ds_read_b128 v[234:237], v218 offset:5120
	ds_read_b128 v[238:241], v218 offset:7168
	ds_read_b128 v[64:67], v219 offset:33792
	ds_read_b128 v[68:71], v219 offset:35840
	ds_read_b128 v[72:75], v219 offset:37888
	ds_read_b128 v[76:79], v219 offset:39936
	s_setprio 1
	v_mfma_f32_16x16x32_bf16 v[140:143], v[16:19], v[32:35], 0
	v_mfma_f32_16x16x32_bf16 v[136:139], v[20:23], v[32:35], 0
	v_mfma_f32_16x16x32_bf16 v[132:135], v[24:27], v[32:35], 0
	v_mfma_f32_16x16x32_bf16 v[128:131], v[28:31], v[32:35], 0
	v_mfma_f32_16x16x32_bf16 v[124:127], v[16:19], v[36:39], 0
	v_mfma_f32_16x16x32_bf16 v[120:123], v[20:23], v[36:39], 0
	v_mfma_f32_16x16x32_bf16 v[116:119], v[24:27], v[36:39], 0
	v_mfma_f32_16x16x32_bf16 v[112:115], v[28:31], v[36:39], 0
	v_mfma_f32_16x16x32_bf16 v[108:111], v[16:19], v[40:43], 0
	v_mfma_f32_16x16x32_bf16 v[104:107], v[20:23], v[40:43], 0
	v_mfma_f32_16x16x32_bf16 v[100:103], v[24:27], v[40:43], 0
	v_mfma_f32_16x16x32_bf16 v[96:99], v[28:31], v[40:43], 0
	v_mfma_f32_16x16x32_bf16 v[92:95], v[16:19], v[44:47], 0
	v_mfma_f32_16x16x32_bf16 v[88:91], v[20:23], v[44:47], 0
	v_mfma_f32_16x16x32_bf16 v[84:87], v[24:27], v[44:47], 0
	v_mfma_f32_16x16x32_bf16 v[80:83], v[28:31], v[44:47], 0
	s_setprio 0
	ds_read_b128 v[156:159], v218 offset:9216
	ds_read_b128 v[152:155], v218 offset:11264
	ds_read_b128 v[148:151], v218 offset:13312
	ds_read_b128 v[144:147], v218 offset:15360
	s_setprio 1
	s_waitcnt lgkmcnt(0)
; #define WAIT_V0() asm volatile("s_waitcnt vmcnt(0)" ::: "memory")
; #define G_STAGE_A(Ap, buf, kt) do { const char* ab_ = (const char*)(Ap) + (size_t)(kt) * 128; \
;       _Pragma("unroll") for (int i = 0; i < 4; ++i) \
;         __builtin_amdgcn_global_load_lds((const unsigned*)(ab_ + soff[i]), (LDSP unsigned*)(G_SA(buf) + wid * 1024 + i * 8192), 16, 0, 0); } while (0)
; #define G_STAGE_B(Bp, buf, kt) do { const char* bb_ = (const char*)(Bp) + (size_t)(kt) * 128; \
;       _Pragma("unroll") for (int i = 0; i < 4; ++i) \
;         __builtin_amdgcn_global_load_lds((const unsigned*)(bb_ + soff[i]), (LDSP unsigned*)(G_SB(buf) + wid * 1024 + i * 8192), 16, 0, 0); } while (0)
; #define G_RDA(AF, buf, ks, mh) do { _Pragma("unroll") for (int m = 0; m < 4; ++m) AF[m] = *(const LDSP bf16x8*)(G_SA(buf) + aoff + ((mh) * 4 + m) * 2048 + (ks) * 1024); } while (0)
; #define G_RDB(BF, buf, ks) do { _Pragma("unroll") for (int n = 0; n < 4; ++n) BF[n] = *(const LDSP bf16x8*)(G_SB(buf) + boff + n * 2048 + (ks) * 1024); } while (0)
; #define G_MMA(AF, BF, mh) do { __builtin_amdgcn_s_setprio(1); \
;             _Pragma("unroll") for (int m = 0; m < 4; ++m) _Pragma("unroll") for (int n = 0; n < 4; ++n) \
;                 acc[(mh) * 4 + m][n] = __builtin_amdgcn_mfma_f32_16x16x32_bf16(BF[n], AF[m], acc[(mh) * 4 + m][n], 0, 0, 0); \
;             __builtin_amdgcn_s_setprio(0); } while (0)
; template <int EK>
; DI void gemm_stream(const Params& p, int l, const bf16_t* __restrict__ A, const bf16_t* __restrict__ Bt, int M, int N, int K, ldsp_t shm) {
;     ...
;         for (int t = 0; t < nt; ++t) {
;             const int cur = t & 1;
;             G_RDA(Aa, cur, 0, 0); G_RDB(Bk0, cur, 0);
;             if (t + 1 < nt) G_STAGE_B(Bb, cur ^ 1, t + 1);
;             else if (has_next) G_STAGE_B(Bb2, cur ^ 1, 0);
;             G_SB0();
;             if (t > 0) G_MMA(Ab_, Bk1, 1);
;             G_SB0();
;             if (t + 1 < nt) G_STAGE_A(Ab, cur ^ 1, t + 1);
;             else if (has_next) G_STAGE_A(Ab2, cur ^ 1, 0);
;             G_RDA(Ab_, cur, 0, 1);
;             G_MMA(Aa, Bk0, 0); G_SB0();
;             G_RDA(Aa, cur, 1, 0); G_RDB(Bk1, cur, 1);
;             G_MMA(Ab_, Bk0, 1); G_SB0();
;             G_RDA(Ab_, cur, 1, 1);
;             G_MMA(Aa, Bk1, 0); G_SB0();
;             asm volatile("s_waitcnt lgkmcnt(0)" ::: "memory");
;             WAIT_V0(); __syncthreads();
;         }
	v_mfma_f32_16x16x32_bf16 v[0:3], v[64:67], v[12:15], v[48:51]
	v_mfma_f32_16x16x32_bf16 v[4:7], v[68:71], v[12:15], v[52:55]
	v_mfma_f32_16x16x32_bf16 v[8:11], v[72:75], v[12:15], v[56:59]
	v_mfma_f32_16x16x32_bf16 v[12:15], v[76:79], v[12:15], v[60:63]
	v_mfma_f32_16x16x32_bf16 v[16:19], v[64:67], v[230:233], v[162:165]
	v_mfma_f32_16x16x32_bf16 v[20:23], v[68:71], v[230:233], v[166:169]
	v_mfma_f32_16x16x32_bf16 v[24:27], v[72:75], v[230:233], v[170:173]
	v_mfma_f32_16x16x32_bf16 v[28:31], v[76:79], v[230:233], v[174:177]
	v_mfma_f32_16x16x32_bf16 v[32:35], v[64:67], v[234:237], v[178:181]
	v_mfma_f32_16x16x32_bf16 v[36:39], v[68:71], v[234:237], v[182:185]
	v_mfma_f32_16x16x32_bf16 v[40:43], v[72:75], v[234:237], v[186:189]
	v_mfma_f32_16x16x32_bf16 v[44:47], v[76:79], v[234:237], v[204:207]
	v_mfma_f32_16x16x32_bf16 v[48:51], v[64:67], v[238:241], v[210:213]
	v_mfma_f32_16x16x32_bf16 v[52:55], v[68:71], v[238:241], v[214:217]
	v_mfma_f32_16x16x32_bf16 v[56:59], v[72:75], v[238:241], v[222:225]
	v_mfma_f32_16x16x32_bf16 v[60:63], v[76:79], v[238:241], v[226:229]
	s_setprio 0
	v_lshlrev_b32_e32 v160, 10, v160
	s_mov_b32 s47, 0xfffe0000
	v_lshlrev_b32_e32 v162, 6, v200
	v_lshlrev_b32_e32 v164, 6, v201
	v_lshlrev_b32_e32 v167, 6, v221
	v_and_or_b32 v160, v160, s47, v191
	v_lshlrev_b32_e32 v166, 13, v161
	s_add_u32 s4, s84, s50
	v_and_or_b32 v162, v162, s47, v191
	v_and_or_b32 v164, v164, s47, v191
	v_and_or_b32 v167, v167, s47, v191
	s_waitcnt lgkmcnt(0)
	v_or3_b32 v168, v160, v166, v190
	v_mov_b32_e32 v169, v193
	s_addc_u32 s5, s85, s51
	v_or3_b32 v170, v162, v166, v190
	v_mov_b32_e32 v171, v193
	v_or3_b32 v172, v164, v166, v190
	v_mov_b32_e32 v173, v193
	v_or3_b32 v174, v167, v166, v190
	v_mov_b32_e32 v175, v193
	s_waitcnt vmcnt(0)
	v_writelane_b32 v255, s52, 12
	v_writelane_b32 v255, s53, 13
	v_writelane_b32 v255, s64, 14
	v_writelane_b32 v255, s65, 15
	v_writelane_b32 v255, s30, 16
	s_mov_b64 s[64:65], s[4:5]
	s_add_u32 s4, s8, s6
	s_addc_u32 s5, s14, s7
	s_mov_b64 s[52:53], s[4:5]
	s_mov_b64 s[4:5], 0
	s_waitcnt vmcnt(0)
	v_lshrrev_b32_e32 v164, 6, v252
	v_lshlrev_b32_e32 v164, 10, v164
	s_nop 0
	v_readfirstlane_b32 s30, v164
	v_and_b32_e32 v165, 63, v252
	v_lshlrev_b32_e32 v165, 4, v165
	s_barrier
	s_and_b32 s6, s43, 0x10000
	v_add_u32_e32 v221, s6, v218
	v_or_b32_e32 v226, s6, v219
	s_xor_b32 s6, s6, 0x10000
	s_add_u32 s6, s6, s30
.LBB0_191:
	ds_read_b128 v[176:179], v221
	ds_read_b128 v[180:183], v221 offset:2048
	ds_read_b128 v[184:187], v221 offset:4096
	ds_read_b128 v[188:191], v221 offset:6144
	s_add_u32 m0, s6, 0x8000
	ds_read_b128 v[204:207], v226 offset:32768
	global_load_lds_dwordx4 v168, s[64:65]
	s_add_u32 m0, s6, 0xa000
	ds_read_b128 v[210:213], v226 offset:34816
	global_load_lds_dwordx4 v170, s[64:65]
	s_add_u32 m0, s6, 0xc000
	ds_read_b128 v[214:217], v226 offset:36864
	global_load_lds_dwordx4 v172, s[64:65]
	s_add_u32 m0, s6, 0xe000
	ds_read_b128 v[222:225], v226 offset:38912
	global_load_lds_dwordx4 v174, s[64:65]
	s_setprio 1
	v_mfma_f32_16x16x32_bf16 v[140:143], v[64:67], v[156:159], v[140:143]
	v_mfma_f32_16x16x32_bf16 v[136:139], v[68:71], v[156:159], v[136:139]
	v_mfma_f32_16x16x32_bf16 v[132:135], v[72:75], v[156:159], v[132:135]
	v_mfma_f32_16x16x32_bf16 v[128:131], v[76:79], v[156:159], v[128:131]
	v_mfma_f32_16x16x32_bf16 v[124:127], v[64:67], v[152:155], v[124:127]
	v_mfma_f32_16x16x32_bf16 v[120:123], v[68:71], v[152:155], v[120:123]
	v_mfma_f32_16x16x32_bf16 v[116:119], v[72:75], v[152:155], v[116:119]
	v_mfma_f32_16x16x32_bf16 v[112:115], v[76:79], v[152:155], v[112:115]
	v_mfma_f32_16x16x32_bf16 v[108:111], v[64:67], v[148:151], v[108:111]
	v_mfma_f32_16x16x32_bf16 v[104:107], v[68:71], v[148:151], v[104:107]
	v_mfma_f32_16x16x32_bf16 v[100:103], v[72:75], v[148:151], v[100:103]
	v_mfma_f32_16x16x32_bf16 v[96:99], v[76:79], v[148:151], v[96:99]
	v_mfma_f32_16x16x32_bf16 v[92:95], v[64:67], v[144:147], v[92:95]
	v_mfma_f32_16x16x32_bf16 v[88:91], v[68:71], v[144:147], v[88:91]
	v_mfma_f32_16x16x32_bf16 v[84:87], v[72:75], v[144:147], v[84:87]
	v_mfma_f32_16x16x32_bf16 v[80:83], v[76:79], v[144:147], v[80:83]
	s_setprio 0
	s_add_u32 m0, s6, 0x0
	s_nop 0
	global_load_lds_dwordx4 v168, s[52:53]
	s_add_u32 m0, s6, 0x2000
	s_nop 0
	global_load_lds_dwordx4 v170, s[52:53]
	s_add_u32 m0, s6, 0x4000
	s_nop 0
	global_load_lds_dwordx4 v172, s[52:53]
	s_add_u32 m0, s6, 0x6000
	s_nop 0
	global_load_lds_dwordx4 v174, s[52:53]
	ds_read_b128 v[144:147], v221 offset:8192
	ds_read_b128 v[148:151], v221 offset:10240
	ds_read_b128 v[152:155], v221 offset:12288
	ds_read_b128 v[156:159], v221 offset:14336
	s_setprio 1
	s_waitcnt lgkmcnt(4)
; #define WAIT_V0() asm volatile("s_waitcnt vmcnt(0)" ::: "memory")
; #define G_STAGE_A(Ap, buf, kt) do { const char* ab_ = (const char*)(Ap) + (size_t)(kt) * 128; \
;       _Pragma("unroll") for (int i = 0; i < 4; ++i) \
;         __builtin_amdgcn_global_load_lds((const unsigned*)(ab_ + soff[i]), (LDSP unsigned*)(G_SA(buf) + wid * 1024 + i * 8192), 16, 0, 0); } while (0)
; #define G_STAGE_B(Bp, buf, kt) do { const char* bb_ = (const char*)(Bp) + (size_t)(kt) * 128; \
;       _Pragma("unroll") for (int i = 0; i < 4; ++i) \
;         __builtin_amdgcn_global_load_lds((const unsigned*)(bb_ + soff[i]), (LDSP unsigned*)(G_SB(buf) + wid * 1024 + i * 8192), 16, 0, 0); } while (0)
; #define G_RDA(AF, buf, ks, mh) do { _Pragma("unroll") for (int m = 0; m < 4; ++m) AF[m] = *(const LDSP bf16x8*)(G_SA(buf) + aoff + ((mh) * 4 + m) * 2048 + (ks) * 1024); } while (0)
; #define G_RDB(BF, buf, ks) do { _Pragma("unroll") for (int n = 0; n < 4; ++n) BF[n] = *(const LDSP bf16x8*)(G_SB(buf) + boff + n * 2048 + (ks) * 1024); } while (0)
; #define G_MMA(AF, BF, mh) do { __builtin_amdgcn_s_setprio(1); \
;             _Pragma("unroll") for (int m = 0; m < 4; ++m) _Pragma("unroll") for (int n = 0; n < 4; ++n) \
;                 acc[(mh) * 4 + m][n] = __builtin_amdgcn_mfma_f32_16x16x32_bf16(BF[n], AF[m], acc[(mh) * 4 + m][n], 0, 0, 0); \
;             __builtin_amdgcn_s_setprio(0); } while (0)
; template <int EK>
; DI void gemm_stream(const Params& p, int l, const bf16_t* __restrict__ A, const bf16_t* __restrict__ Bt, int M, int N, int K, ldsp_t shm) {
;     ...
;         for (int t = 0; t < nt; ++t) {
;             const int cur = t & 1;
;             G_RDA(Aa, cur, 0, 0); G_RDB(Bk0, cur, 0);
;             if (t + 1 < nt) G_STAGE_B(Bb, cur ^ 1, t + 1);
;             else if (has_next) G_STAGE_B(Bb2, cur ^ 1, 0);
;             G_SB0();
;             if (t > 0) G_MMA(Ab_, Bk1, 1);
;             G_SB0();
;             if (t + 1 < nt) G_STAGE_A(Ab, cur ^ 1, t + 1);
;             else if (has_next) G_STAGE_A(Ab2, cur ^ 1, 0);
;             G_RDA(Ab_, cur, 0, 1);
;             G_MMA(Aa, Bk0, 0); G_SB0();
;             G_RDA(Aa, cur, 1, 0); G_RDB(Bk1, cur, 1);
;             G_MMA(Ab_, Bk0, 1); G_SB0();
;             G_RDA(Ab_, cur, 1, 1);
;             G_MMA(Aa, Bk1, 0); G_SB0();
;             asm volatile("s_waitcnt lgkmcnt(0)" ::: "memory");
;             WAIT_V0(); __syncthreads();
;         }
	v_mfma_f32_16x16x32_bf16 v[0:3], v[204:207], v[176:179], v[0:3]
	v_mfma_f32_16x16x32_bf16 v[4:7], v[210:213], v[176:179], v[4:7]
	v_mfma_f32_16x16x32_bf16 v[8:11], v[214:217], v[176:179], v[8:11]
	v_mfma_f32_16x16x32_bf16 v[12:15], v[222:225], v[176:179], v[12:15]
	v_mfma_f32_16x16x32_bf16 v[16:19], v[204:207], v[180:183], v[16:19]
	v_mfma_f32_16x16x32_bf16 v[20:23], v[210:213], v[180:183], v[20:23]
	v_mfma_f32_16x16x32_bf16 v[24:27], v[214:217], v[180:183], v[24:27]
	v_mfma_f32_16x16x32_bf16 v[28:31], v[222:225], v[180:183], v[28:31]
	v_mfma_f32_16x16x32_bf16 v[32:35], v[204:207], v[184:187], v[32:35]
	v_mfma_f32_16x16x32_bf16 v[36:39], v[210:213], v[184:187], v[36:39]
	v_mfma_f32_16x16x32_bf16 v[40:43], v[214:217], v[184:187], v[40:43]
	v_mfma_f32_16x16x32_bf16 v[44:47], v[222:225], v[184:187], v[44:47]
	v_mfma_f32_16x16x32_bf16 v[48:51], v[204:207], v[188:191], v[48:51]
	v_mfma_f32_16x16x32_bf16 v[52:55], v[210:213], v[188:191], v[52:55]
	v_mfma_f32_16x16x32_bf16 v[56:59], v[214:217], v[188:191], v[56:59]
	v_mfma_f32_16x16x32_bf16 v[60:63], v[222:225], v[188:191], v[60:63]
	s_setprio 0
	ds_read_b128 v[176:179], v221 offset:1024
	ds_read_b128 v[180:183], v221 offset:3072
	ds_read_b128 v[184:187], v221 offset:5120
	ds_read_b128 v[188:191], v221 offset:7168
	ds_read_b128 v[64:67], v226 offset:33792
	ds_read_b128 v[68:71], v226 offset:35840
	ds_read_b128 v[72:75], v226 offset:37888
	ds_read_b128 v[76:79], v226 offset:39936
	s_setprio 1
	s_waitcnt lgkmcnt(8)
	v_mfma_f32_16x16x32_bf16 v[140:143], v[204:207], v[144:147], v[140:143]
	v_mfma_f32_16x16x32_bf16 v[136:139], v[210:213], v[144:147], v[136:139]
	v_mfma_f32_16x16x32_bf16 v[132:135], v[214:217], v[144:147], v[132:135]
	v_mfma_f32_16x16x32_bf16 v[128:131], v[222:225], v[144:147], v[128:131]
	v_mfma_f32_16x16x32_bf16 v[124:127], v[204:207], v[148:151], v[124:127]
	v_mfma_f32_16x16x32_bf16 v[120:123], v[210:213], v[148:151], v[120:123]
	v_mfma_f32_16x16x32_bf16 v[116:119], v[214:217], v[148:151], v[116:119]
	v_mfma_f32_16x16x32_bf16 v[112:115], v[222:225], v[148:151], v[112:115]
	v_mfma_f32_16x16x32_bf16 v[108:111], v[204:207], v[152:155], v[108:111]
	v_mfma_f32_16x16x32_bf16 v[104:107], v[210:213], v[152:155], v[104:107]
	v_mfma_f32_16x16x32_bf16 v[100:103], v[214:217], v[152:155], v[100:103]
	v_mfma_f32_16x16x32_bf16 v[96:99], v[222:225], v[152:155], v[96:99]
	v_mfma_f32_16x16x32_bf16 v[92:95], v[204:207], v[156:159], v[92:95]
	v_mfma_f32_16x16x32_bf16 v[88:91], v[210:213], v[156:159], v[88:91]
	v_mfma_f32_16x16x32_bf16 v[84:87], v[214:217], v[156:159], v[84:87]
	v_mfma_f32_16x16x32_bf16 v[80:83], v[222:225], v[156:159], v[80:83]
	s_setprio 0
	ds_read_b128 v[156:159], v221 offset:9216
	ds_read_b128 v[152:155], v221 offset:11264
	ds_read_b128 v[148:151], v221 offset:13312
	ds_read_b128 v[144:147], v221 offset:15360
	s_setprio 1
	s_waitcnt lgkmcnt(4)
	v_mfma_f32_16x16x32_bf16 v[0:3], v[64:67], v[176:179], v[0:3]
	v_mfma_f32_16x16x32_bf16 v[4:7], v[68:71], v[176:179], v[4:7]
	v_mfma_f32_16x16x32_bf16 v[8:11], v[72:75], v[176:179], v[8:11]
	v_mfma_f32_16x16x32_bf16 v[12:15], v[76:79], v[176:179], v[12:15]
	v_mfma_f32_16x16x32_bf16 v[16:19], v[64:67], v[180:183], v[16:19]
	v_mfma_f32_16x16x32_bf16 v[20:23], v[68:71], v[180:183], v[20:23]
	v_mfma_f32_16x16x32_bf16 v[24:27], v[72:75], v[180:183], v[24:27]
	v_mfma_f32_16x16x32_bf16 v[28:31], v[76:79], v[180:183], v[28:31]
	v_mfma_f32_16x16x32_bf16 v[32:35], v[64:67], v[184:187], v[32:35]
	v_mfma_f32_16x16x32_bf16 v[36:39], v[68:71], v[184:187], v[36:39]
	v_mfma_f32_16x16x32_bf16 v[40:43], v[72:75], v[184:187], v[40:43]
	v_mfma_f32_16x16x32_bf16 v[44:47], v[76:79], v[184:187], v[44:47]
	v_mfma_f32_16x16x32_bf16 v[48:51], v[64:67], v[188:191], v[48:51]
	v_mfma_f32_16x16x32_bf16 v[52:55], v[68:71], v[188:191], v[52:55]
	v_mfma_f32_16x16x32_bf16 v[56:59], v[72:75], v[188:191], v[56:59]
	v_mfma_f32_16x16x32_bf16 v[60:63], v[76:79], v[188:191], v[60:63]
	s_setprio 0
	s_waitcnt lgkmcnt(0)
	s_add_u32 s52, s52, 0x80
	s_addc_u32 s53, s53, 0
	s_add_u32 s64, s64, 0x80
	s_addc_u32 s65, s65, 0
	s_add_u32 s4, s4, 0x80
	s_addc_u32 s5, s5, 0
	s_add_i32 s43, s43, 0x10000
	s_and_b32 s6, s43, 0x10000
	v_add_u32_e32 v221, s6, v218
	v_or_b32_e32 v226, s6, v219
	s_xor_b32 s6, s6, 0x10000
	s_add_u32 s6, s6, s30
	s_cmpk_eq_i32 s4, 0x1f00
	s_waitcnt vmcnt(0)
	s_barrier
	s_cbranch_scc0 .LBB0_191
	v_readlane_b32 s52, v255, 12
	v_readlane_b32 s53, v255, 13
	v_readlane_b32 s64, v255, 14
	v_readlane_b32 s65, v255, 15
	v_readlane_b32 s30, v255, 16
	v_add_u32_e32 v160, 0x10000, v218
	v_add_u32_e32 v161, 0x10800, v218
	ds_read_b128 v[188:191], v160
	ds_read_b128 v[180:183], v161
	v_add_u32_e32 v160, 0x11000, v218
	v_add_u32_e32 v161, 0x11800, v218
	ds_read_b128 v[184:187], v160
	ds_read_b128 v[176:179], v161
	v_or_b32_e32 v160, 0x18000, v219
	v_add_u32_e32 v164, 0x18800, v219
	v_add_u32_e32 v168, 0x19000, v219
	v_add_u32_e32 v172, 0x19800, v219
	ds_read_b128 v[160:163], v160
	ds_read_b128 v[164:167], v164
	ds_read_b128 v[168:171], v168
	ds_read_b128 v[172:175], v172
	s_ashr_i32 s47, s46, 31
	v_cndmask_b32_e64 v200, 0, 1, s[34:35]
	v_cmp_ne_u32_e64 s[4:5], 1, v200
	s_andn2_b64 vcc, exec, s[34:35]
	s_lshl_b64 s[50:51], s[46:47], 21
	s_cbranch_vccnz .LBB0_194
	s_add_u32 s6, s9, s50
	s_addc_u32 s7, s31, s51
	v_add_u32_e32 v212, 0x8000, v220
	v_lshl_add_u64 v[200:201], s[6:7], 0, v[192:193]
	v_lshl_add_u64 v[204:205], s[6:7], 0, v[194:195]
	v_lshl_add_u64 v[206:207], s[6:7], 0, v[196:197]
	v_lshl_add_u64 v[210:211], s[6:7], 0, v[198:199]
	v_add_u32_e32 v215, 0xa000, v220
	v_readfirstlane_b32 s6, v212
	v_add_u32_e32 v214, 0xc000, v220
	s_mov_b32 m0, s6
	v_readfirstlane_b32 s6, v215
	v_add_u32_e32 v213, 0xe000, v220
	global_load_lds_dwordx4 v[200:201], off
	s_mov_b32 m0, s6
	v_readfirstlane_b32 s6, v214
	global_load_lds_dwordx4 v[204:205], off
	s_mov_b32 m0, s6
	v_readfirstlane_b32 s6, v213
	global_load_lds_dwordx4 v[206:207], off
	s_mov_b32 m0, s6
	s_nop 0
	global_load_lds_dwordx4 v[210:211], off

; #define WAIT_V0() asm volatile("s_waitcnt vmcnt(0)" ::: "memory")
; #define G_LANE_SETUP() \
;     int tid_ = threadIdx.x; \
;     asm volatile("" : "+v"(tid_));    \
;     const int wid = tid_ >> 6, lane = tid_ & 63, wr = wid >> 2, wc = wid & 3, fr = lane & 15, fq = lane >> 4; \
;     unsigned soff[4];        \
;     _Pragma("unroll") for (int i = 0; i < 4; ++i) { int sR, sC; stage_rc2(wid * 1024 + i * 8192 + lane * 16, sR, sC); soff[i] = (unsigned)(sR * K + sC) * 2u; }
; #define G_SB0() __builtin_amdgcn_sched_barrier(0)
; template <int EK>
; DI void gemm_stream(const Params& p, int l, const bf16_t* __restrict__ A, const bf16_t* __restrict__ Bt, int M, int N, int K, ldsp_t shm) {
;     ...
;     const int nt = K / 64;
;     int pm, pn;
;     tile_coords(L, nM, nN, pm, pn);
;     const bf16_t* Ab = A + (size_t)pm * 256 * K;
;     const bf16_t* Bb = Bt + (size_t)pn * 256 * K;
;     { G_LANE_SETUP(); (void)wr; (void)wc; (void)fr; (void)fq; G_STAGE(Ab, Bb, 0, 0); WAIT_V0(); __syncthreads(); }
;     while (true) {
;         G_LANE_SETUP();
;         const int aoff = lds_byte2(wr * 128 + fr, fq * 8), boff = lds_byte2(wc * 64 + fr, fq * 8);
;         f32x4 acc[8][4];
; #pragma unroll
;         for (int m = 0; m < 8; ++m)
; #pragma unroll
;             for (int n = 0; n < 4; ++n) acc[m][n] = (f32x4){0.f, 0.f, 0.f, 0.f};
;         const int Ln = L + gridDim.x;
;         const bool has_next = Ln < nwg;
;         int pm2 = pm, pn2 = pn;
;         if (has_next) tile_coords(Ln, nM, nN, pm2, pn2);
;         const bf16_t* Ab2 = A + (size_t)pm2 * 256 * K;
;         const bf16_t* Bb2 = Bt + (size_t)pn2 * 256 * K;
;         bf16x8 Aa[4], Ab_[4], Bk0[4], Bk1[4];
;     ...
;         for (int t = 0; t < nt; ++t) {
;             const int cur = t & 1;
;             G_RDA(Aa, cur, 0, 0); G_RDB(Bk0, cur, 0);
;             if (t + 1 < nt) G_STAGE_B(Bb, cur ^ 1, t + 1);
;             else if (has_next) G_STAGE_B(Bb2, cur ^ 1, 0);
;             G_SB0();
;             if (t > 0) G_MMA(Ab_, Bk1, 1);
;             G_SB0();
;             if (t + 1 < nt) G_STAGE_A(Ab, cur ^ 1, t + 1);
;             else if (has_next) G_STAGE_A(Ab2, cur ^ 1, 0);
;             G_RDA(Ab_, cur, 0, 1);
;             G_MMA(Aa, Bk0, 0); G_SB0();
;             G_RDA(Aa, cur, 1, 0); G_RDB(Bk1, cur, 1);
;             G_MMA(Ab_, Bk0, 1); G_SB0();
;             G_RDA(Ab_, cur, 1, 1);
;             G_MMA(Aa, Bk1, 0); G_SB0();
.LBB0_263:
	v_lshlrev_b32_e32 v0, 4, v160
	v_and_b32_e32 v1, 32, v160
	v_bfe_u32 v161, v160, 2, 4
	v_and_b32_e32 v190, 64, v160
	v_bitop3_b32 v191, v0, v1, 48 bitop3:0x6c
	v_lshrrev_b32_e32 v2, 3, v160
	v_or_b32_e32 v1, v191, v190
	v_and_or_b32 v2, v2, s86, v161
	v_add_u32_e32 v200, 0x2000, v0
	v_lshl_or_b32 v192, v2, 11, v1
	v_lshrrev_b32_e32 v2, 7, v200
	v_and_or_b32 v2, v2, s86, v161
	v_add_u32_e32 v201, 0x4000, v0
	v_add_u32_e32 v204, 0x6000, v0
	v_and_b32_e32 v220, 0xfffffc00, v0
	v_lshl_or_b32 v194, v2, 11, v1
	v_lshrrev_b32_e32 v2, 7, v201
	v_lshrrev_b32_e32 v0, 7, v204
	v_and_or_b32 v2, v2, s86, v161
	v_and_or_b32 v0, v0, s86, v161
	v_lshl_or_b32 v196, v2, 11, v1
	v_lshl_or_b32 v198, v0, 11, v1
	v_lshlrev_b32_e32 v1, 6, v160
	v_lshlrev_b32_e32 v4, 2, v160
	v_and_b32_e32 v0, 48, v160
	v_and_b32_e32 v2, 0x3c0, v1
	v_and_b32_e32 v4, 32, v4
	v_bitop3_b32 v0, v2, v4, v0 bitop3:0x36
	s_movk_i32 s4, 0xc000
	v_and_or_b32 v218, v1, s4, v0
	s_add_u32 s4, s14, s46
	s_addc_u32 s5, s15, s47
	v_add_u32_e32 v34, 0x18000, v220
	v_lshl_add_u64 v[32:33], s[4:5], 0, v[192:193]
	v_readfirstlane_b32 s8, v34
	v_lshlrev_b32_e32 v3, 7, v160
	v_lshl_add_u64 v[32:33], v[32:33], 0, s[0:1]
	s_mov_b32 m0, s8
	v_mov_b32_e32 v195, v193
	v_add_u32_e32 v34, 0x1a000, v220
	v_and_or_b32 v219, v3, s28, v0
	ds_read_b128 v[0:3], v218
	ds_read_b128 v[4:7], v218 offset:2048
	ds_read_b128 v[8:11], v218 offset:4096
	ds_read_b128 v[12:15], v218 offset:6144
	ds_read_b128 v[16:19], v219 offset:32768
	ds_read_b128 v[20:23], v219 offset:34816
	ds_read_b128 v[24:27], v219 offset:36864
	ds_read_b128 v[28:31], v219 offset:38912
	global_load_lds_dwordx4 v[32:33], off
	v_lshl_add_u64 v[32:33], s[4:5], 0, v[194:195]
	v_readfirstlane_b32 s8, v34
	v_lshl_add_u64 v[32:33], v[32:33], 0, s[0:1]
	s_mov_b32 m0, s8
	v_mov_b32_e32 v197, v193
	v_add_u32_e32 v34, 0x1c000, v220
	global_load_lds_dwordx4 v[32:33], off
	v_lshl_add_u64 v[32:33], s[4:5], 0, v[196:197]
	v_readfirstlane_b32 s8, v34
	v_lshl_add_u64 v[32:33], v[32:33], 0, s[0:1]
	s_mov_b32 m0, s8
	v_mov_b32_e32 v199, v193
	v_add_u32_e32 v34, 0x1e000, v220
	global_load_lds_dwordx4 v[32:33], off
	v_lshl_add_u64 v[32:33], s[4:5], 0, v[198:199]
	v_readfirstlane_b32 s4, v34
	v_lshl_add_u64 v[32:33], v[32:33], 0, s[0:1]
	s_mov_b32 m0, s4
	s_nop 0
	global_load_lds_dwordx4 v[32:33], off
	s_add_u32 s4, s82, s36
	s_addc_u32 s5, s83, s37
	v_add_u32_e32 v34, 0x10000, v220
	v_lshl_add_u64 v[32:33], s[4:5], 0, v[192:193]
	v_readfirstlane_b32 s8, v34
	v_lshl_add_u64 v[32:33], v[32:33], 0, s[0:1]
	s_mov_b32 m0, s8
	v_add_u32_e32 v34, 0x12000, v220
	global_load_lds_dwordx4 v[32:33], off
	v_lshl_add_u64 v[32:33], s[4:5], 0, v[194:195]
	v_readfirstlane_b32 s8, v34
	v_lshl_add_u64 v[32:33], v[32:33], 0, s[0:1]
	s_mov_b32 m0, s8
	v_add_u32_e32 v34, 0x14000, v220
	global_load_lds_dwordx4 v[32:33], off
	v_lshl_add_u64 v[32:33], s[4:5], 0, v[196:197]
	v_readfirstlane_b32 s8, v34
	v_lshl_add_u64 v[32:33], v[32:33], 0, s[0:1]
	s_mov_b32 m0, s8
	v_add_u32_e32 v34, 0x16000, v220
	global_load_lds_dwordx4 v[32:33], off
	v_lshl_add_u64 v[32:33], s[4:5], 0, v[198:199]
	v_readfirstlane_b32 s4, v34
	v_lshl_add_u64 v[32:33], v[32:33], 0, s[0:1]
	s_mov_b32 m0, s4
	s_mov_b32 s8, 0x10000
	global_load_lds_dwordx4 v[32:33], off
	ds_read_b128 v[32:35], v218 offset:8192
	ds_read_b128 v[36:39], v218 offset:10240
	ds_read_b128 v[40:43], v218 offset:12288
	ds_read_b128 v[44:47], v218 offset:14336
	s_setprio 1
	s_waitcnt lgkmcnt(0)
	v_mfma_f32_16x16x32_bf16 v[48:51], v[16:19], v[0:3], 0
	v_mfma_f32_16x16x32_bf16 v[52:55], v[20:23], v[0:3], 0
	v_mfma_f32_16x16x32_bf16 v[56:59], v[24:27], v[0:3], 0
	v_mfma_f32_16x16x32_bf16 v[60:63], v[28:31], v[0:3], 0
	v_mfma_f32_16x16x32_bf16 v[162:165], v[16:19], v[4:7], 0
	v_mfma_f32_16x16x32_bf16 v[166:169], v[20:23], v[4:7], 0
	v_mfma_f32_16x16x32_bf16 v[170:173], v[24:27], v[4:7], 0
	v_mfma_f32_16x16x32_bf16 v[174:177], v[28:31], v[4:7], 0
	v_mfma_f32_16x16x32_bf16 v[178:181], v[16:19], v[8:11], 0
	v_mfma_f32_16x16x32_bf16 v[182:185], v[20:23], v[8:11], 0
	v_mfma_f32_16x16x32_bf16 v[186:189], v[24:27], v[8:11], 0
	v_mfma_f32_16x16x32_bf16 v[222:225], v[28:31], v[8:11], 0
	v_mfma_f32_16x16x32_bf16 v[226:229], v[16:19], v[12:15], 0
	v_mfma_f32_16x16x32_bf16 v[230:233], v[20:23], v[12:15], 0
	v_mfma_f32_16x16x32_bf16 v[234:237], v[24:27], v[12:15], 0
	v_mfma_f32_16x16x32_bf16 v[238:241], v[28:31], v[12:15], 0
	s_setprio 0
	ds_read_b128 v[12:15], v218 offset:1024
	ds_read_b128 v[242:245], v218 offset:3072
	ds_read_b128 v[246:249], v218 offset:5120
	ds_read_b128 v[214:217], v218 offset:7168
	ds_read_b128 v[64:67], v219 offset:33792
	ds_read_b128 v[68:71], v219 offset:35840
	ds_read_b128 v[76:79], v219 offset:37888
	ds_read_b128 v[72:75], v219 offset:39936
	s_setprio 1
	v_mfma_f32_16x16x32_bf16 v[128:131], v[16:19], v[32:35], 0
	v_mfma_f32_16x16x32_bf16 v[124:127], v[20:23], v[32:35], 0
	v_mfma_f32_16x16x32_bf16 v[120:123], v[24:27], v[32:35], 0
	v_mfma_f32_16x16x32_bf16 v[116:119], v[28:31], v[32:35], 0
	v_mfma_f32_16x16x32_bf16 v[112:115], v[16:19], v[36:39], 0
	v_mfma_f32_16x16x32_bf16 v[108:111], v[20:23], v[36:39], 0
	v_mfma_f32_16x16x32_bf16 v[104:107], v[24:27], v[36:39], 0
	v_mfma_f32_16x16x32_bf16 v[100:103], v[28:31], v[36:39], 0
	v_mfma_f32_16x16x32_bf16 v[96:99], v[16:19], v[40:43], 0
	v_mfma_f32_16x16x32_bf16 v[92:95], v[20:23], v[40:43], 0
	v_mfma_f32_16x16x32_bf16 v[88:91], v[24:27], v[40:43], 0
	v_mfma_f32_16x16x32_bf16 v[84:87], v[28:31], v[40:43], 0
	v_mfma_f32_16x16x32_bf16 v[132:135], v[16:19], v[44:47], 0
	v_mfma_f32_16x16x32_bf16 v[136:139], v[20:23], v[44:47], 0
	v_mfma_f32_16x16x32_bf16 v[140:143], v[24:27], v[44:47], 0
	v_mfma_f32_16x16x32_bf16 v[80:83], v[28:31], v[44:47], 0
	s_setprio 0
	ds_read_b128 v[156:159], v218 offset:9216
	ds_read_b128 v[152:155], v218 offset:11264
	ds_read_b128 v[148:151], v218 offset:13312
	ds_read_b128 v[144:147], v218 offset:15360
	s_setprio 1
	s_waitcnt lgkmcnt(0)
; #define WAIT_V0() asm volatile("s_waitcnt vmcnt(0)" ::: "memory")
; #define G_STAGE_A(Ap, buf, kt) do { const char* ab_ = (const char*)(Ap) + (size_t)(kt) * 128; \
;       _Pragma("unroll") for (int i = 0; i < 4; ++i) \
;         __builtin_amdgcn_global_load_lds((const unsigned*)(ab_ + soff[i]), (LDSP unsigned*)(G_SA(buf) + wid * 1024 + i * 8192), 16, 0, 0); } while (0)
; #define G_STAGE_B(Bp, buf, kt) do { const char* bb_ = (const char*)(Bp) + (size_t)(kt) * 128; \
;       _Pragma("unroll") for (int i = 0; i < 4; ++i) \
;         __builtin_amdgcn_global_load_lds((const unsigned*)(bb_ + soff[i]), (LDSP unsigned*)(G_SB(buf) + wid * 1024 + i * 8192), 16, 0, 0); } while (0)
; #define G_RDA(AF, buf, ks, mh) do { _Pragma("unroll") for (int m = 0; m < 4; ++m) AF[m] = *(const LDSP bf16x8*)(G_SA(buf) + aoff + ((mh) * 4 + m) * 2048 + (ks) * 1024); } while (0)
; #define G_RDB(BF, buf, ks) do { _Pragma("unroll") for (int n = 0; n < 4; ++n) BF[n] = *(const LDSP bf16x8*)(G_SB(buf) + boff + n * 2048 + (ks) * 1024); } while (0)
; #define G_MMA(AF, BF, mh) do { __builtin_amdgcn_s_setprio(1); \
;             _Pragma("unroll") for (int m = 0; m < 4; ++m) _Pragma("unroll") for (int n = 0; n < 4; ++n) \
;                 acc[(mh) * 4 + m][n] = __builtin_amdgcn_mfma_f32_16x16x32_bf16(BF[n], AF[m], acc[(mh) * 4 + m][n], 0, 0, 0); \
;             __builtin_amdgcn_s_setprio(0); } while (0)
; template <int EK>
; DI void gemm_stream(const Params& p, int l, const bf16_t* __restrict__ A, const bf16_t* __restrict__ Bt, int M, int N, int K, ldsp_t shm) {
;     ...
;         for (int t = 0; t < nt; ++t) {
;             const int cur = t & 1;
;             G_RDA(Aa, cur, 0, 0); G_RDB(Bk0, cur, 0);
;             if (t + 1 < nt) G_STAGE_B(Bb, cur ^ 1, t + 1);
;             else if (has_next) G_STAGE_B(Bb2, cur ^ 1, 0);
;             G_SB0();
;             if (t > 0) G_MMA(Ab_, Bk1, 1);
;             G_SB0();
;             if (t + 1 < nt) G_STAGE_A(Ab, cur ^ 1, t + 1);
;             else if (has_next) G_STAGE_A(Ab2, cur ^ 1, 0);
;             G_RDA(Ab_, cur, 0, 1);
;             G_MMA(Aa, Bk0, 0); G_SB0();
;             G_RDA(Aa, cur, 1, 0); G_RDB(Bk1, cur, 1);
;             G_MMA(Ab_, Bk0, 1); G_SB0();
;             G_RDA(Ab_, cur, 1, 1);
;             G_MMA(Aa, Bk1, 0); G_SB0();
;             asm volatile("s_waitcnt lgkmcnt(0)" ::: "memory");
;             WAIT_V0(); __syncthreads();
;         }
	v_mfma_f32_16x16x32_bf16 v[0:3], v[64:67], v[12:15], v[48:51]
	v_mfma_f32_16x16x32_bf16 v[4:7], v[68:71], v[12:15], v[52:55]
	v_mfma_f32_16x16x32_bf16 v[8:11], v[76:79], v[12:15], v[56:59]
	v_mfma_f32_16x16x32_bf16 v[12:15], v[72:75], v[12:15], v[60:63]
	v_mfma_f32_16x16x32_bf16 v[16:19], v[64:67], v[242:245], v[162:165]
	v_mfma_f32_16x16x32_bf16 v[20:23], v[68:71], v[242:245], v[166:169]
	v_mfma_f32_16x16x32_bf16 v[24:27], v[76:79], v[242:245], v[170:173]
	v_mfma_f32_16x16x32_bf16 v[28:31], v[72:75], v[242:245], v[174:177]
	v_mfma_f32_16x16x32_bf16 v[32:35], v[64:67], v[246:249], v[178:181]
	v_mfma_f32_16x16x32_bf16 v[36:39], v[68:71], v[246:249], v[182:185]
	v_mfma_f32_16x16x32_bf16 v[40:43], v[76:79], v[246:249], v[186:189]
	v_mfma_f32_16x16x32_bf16 v[44:47], v[72:75], v[246:249], v[222:225]
	v_mfma_f32_16x16x32_bf16 v[48:51], v[64:67], v[214:217], v[226:229]
	v_mfma_f32_16x16x32_bf16 v[52:55], v[68:71], v[214:217], v[230:233]
	v_mfma_f32_16x16x32_bf16 v[56:59], v[76:79], v[214:217], v[234:237]
	v_mfma_f32_16x16x32_bf16 v[60:63], v[72:75], v[214:217], v[238:241]
	s_setprio 0
	v_lshlrev_b32_e32 v160, 8, v160
	s_movk_i32 s9, 0x8000
	v_readlane_b32 s4, v255, 10
	v_lshlrev_b32_e32 v162, 4, v200
	v_lshlrev_b32_e32 v164, 4, v201
	v_lshlrev_b32_e32 v167, 4, v204
	v_and_or_b32 v160, v160, s9, v191
	v_lshlrev_b32_e32 v166, 11, v161
	s_add_u32 s4, s4, s46
	v_readlane_b32 s5, v255, 7
	v_and_or_b32 v162, v162, s9, v191
	v_and_or_b32 v164, v164, s9, v191
	v_and_or_b32 v167, v167, s9, v191
	s_waitcnt lgkmcnt(0)
	v_or3_b32 v168, v160, v166, v190
	v_mov_b32_e32 v169, v193
	s_addc_u32 s5, s5, s47
	v_or3_b32 v170, v162, v166, v190
	v_mov_b32_e32 v171, v193
	v_or3_b32 v172, v164, v166, v190
	v_mov_b32_e32 v173, v193
	v_or3_b32 v174, v167, v166, v190
	v_mov_b32_e32 v175, v193
	s_waitcnt vmcnt(0)
	v_writelane_b32 v255, s52, 12
	v_writelane_b32 v255, s53, 13
	v_writelane_b32 v255, s64, 14
	v_writelane_b32 v255, s65, 15
	v_writelane_b32 v255, s30, 16
	s_mov_b64 s[64:65], s[4:5]
	s_add_u32 s4, s38, s36
	s_addc_u32 s5, s39, s37
	s_mov_b64 s[52:53], s[4:5]
	s_mov_b64 s[4:5], 0
	s_waitcnt vmcnt(0)
	v_lshrrev_b32_e32 v164, 6, v252
	v_lshlrev_b32_e32 v164, 10, v164
	s_nop 0
	v_readfirstlane_b32 s30, v164
	v_and_b32_e32 v165, 63, v252
	v_lshlrev_b32_e32 v165, 4, v165
	s_barrier
	s_and_b32 s9, s8, 0x10000
	v_add_u32_e32 v221, s9, v218
	v_or_b32_e32 v226, s9, v219
	s_xor_b32 s9, s9, 0x10000
	s_add_u32 s9, s9, s30
.LBB0_264:
	ds_read_b128 v[176:179], v221
	ds_read_b128 v[180:183], v221 offset:2048
	ds_read_b128 v[184:187], v221 offset:4096
	ds_read_b128 v[188:191], v221 offset:6144
	s_add_u32 m0, s9, 0x8000
	ds_read_b128 v[204:207], v226 offset:32768
	global_load_lds_dwordx4 v168, s[64:65]
	s_add_u32 m0, s9, 0xa000
	ds_read_b128 v[210:213], v226 offset:34816
	global_load_lds_dwordx4 v170, s[64:65]
	s_add_u32 m0, s9, 0xc000
	ds_read_b128 v[214:217], v226 offset:36864
	global_load_lds_dwordx4 v172, s[64:65]
	s_add_u32 m0, s9, 0xe000
	ds_read_b128 v[222:225], v226 offset:38912
	global_load_lds_dwordx4 v174, s[64:65]
	s_setprio 1
	v_mfma_f32_16x16x32_bf16 v[128:131], v[64:67], v[156:159], v[128:131]
	v_mfma_f32_16x16x32_bf16 v[124:127], v[68:71], v[156:159], v[124:127]
	v_mfma_f32_16x16x32_bf16 v[120:123], v[76:79], v[156:159], v[120:123]
	v_mfma_f32_16x16x32_bf16 v[116:119], v[72:75], v[156:159], v[116:119]
	v_mfma_f32_16x16x32_bf16 v[112:115], v[64:67], v[152:155], v[112:115]
	v_mfma_f32_16x16x32_bf16 v[108:111], v[68:71], v[152:155], v[108:111]
	v_mfma_f32_16x16x32_bf16 v[104:107], v[76:79], v[152:155], v[104:107]
	v_mfma_f32_16x16x32_bf16 v[100:103], v[72:75], v[152:155], v[100:103]
	v_mfma_f32_16x16x32_bf16 v[96:99], v[64:67], v[148:151], v[96:99]
	v_mfma_f32_16x16x32_bf16 v[92:95], v[68:71], v[148:151], v[92:95]
	v_mfma_f32_16x16x32_bf16 v[88:91], v[76:79], v[148:151], v[88:91]
	v_mfma_f32_16x16x32_bf16 v[84:87], v[72:75], v[148:151], v[84:87]
	v_mfma_f32_16x16x32_bf16 v[132:135], v[64:67], v[144:147], v[132:135]
	v_mfma_f32_16x16x32_bf16 v[136:139], v[68:71], v[144:147], v[136:139]
	v_mfma_f32_16x16x32_bf16 v[140:143], v[76:79], v[144:147], v[140:143]
	v_mfma_f32_16x16x32_bf16 v[80:83], v[72:75], v[144:147], v[80:83]
	s_setprio 0
	s_add_u32 m0, s9, 0x0
	s_nop 0
	global_load_lds_dwordx4 v168, s[52:53]
	s_add_u32 m0, s9, 0x2000
	s_nop 0
	global_load_lds_dwordx4 v170, s[52:53]
	s_add_u32 m0, s9, 0x4000
	s_nop 0
	global_load_lds_dwordx4 v172, s[52:53]
	s_add_u32 m0, s9, 0x6000
	s_nop 0
	global_load_lds_dwordx4 v174, s[52:53]
	ds_read_b128 v[144:147], v221 offset:8192
	ds_read_b128 v[148:151], v221 offset:10240
	ds_read_b128 v[152:155], v221 offset:12288
	ds_read_b128 v[156:159], v221 offset:14336
	s_setprio 1
	s_waitcnt lgkmcnt(4)
; #define WAIT_V0() asm volatile("s_waitcnt vmcnt(0)" ::: "memory")
; #define G_STAGE_A(Ap, buf, kt) do { const char* ab_ = (const char*)(Ap) + (size_t)(kt) * 128; \
;       _Pragma("unroll") for (int i = 0; i < 4; ++i) \
;         __builtin_amdgcn_global_load_lds((const unsigned*)(ab_ + soff[i]), (LDSP unsigned*)(G_SA(buf) + wid * 1024 + i * 8192), 16, 0, 0); } while (0)
; #define G_STAGE_B(Bp, buf, kt) do { const char* bb_ = (const char*)(Bp) + (size_t)(kt) * 128; \
;       _Pragma("unroll") for (int i = 0; i < 4; ++i) \
;         __builtin_amdgcn_global_load_lds((const unsigned*)(bb_ + soff[i]), (LDSP unsigned*)(G_SB(buf) + wid * 1024 + i * 8192), 16, 0, 0); } while (0)
; #define G_RDA(AF, buf, ks, mh) do { _Pragma("unroll") for (int m = 0; m < 4; ++m) AF[m] = *(const LDSP bf16x8*)(G_SA(buf) + aoff + ((mh) * 4 + m) * 2048 + (ks) * 1024); } while (0)
; #define G_RDB(BF, buf, ks) do { _Pragma("unroll") for (int n = 0; n < 4; ++n) BF[n] = *(const LDSP bf16x8*)(G_SB(buf) + boff + n * 2048 + (ks) * 1024); } while (0)
; #define G_MMA(AF, BF, mh) do { __builtin_amdgcn_s_setprio(1); \
;             _Pragma("unroll") for (int m = 0; m < 4; ++m) _Pragma("unroll") for (int n = 0; n < 4; ++n) \
;                 acc[(mh) * 4 + m][n] = __builtin_amdgcn_mfma_f32_16x16x32_bf16(BF[n], AF[m], acc[(mh) * 4 + m][n], 0, 0, 0); \
;             __builtin_amdgcn_s_setprio(0); } while (0)
; template <int EK>
; DI void gemm_stream(const Params& p, int l, const bf16_t* __restrict__ A, const bf16_t* __restrict__ Bt, int M, int N, int K, ldsp_t shm) {
;     ...
;         for (int t = 0; t < nt; ++t) {
;             const int cur = t & 1;
;             G_RDA(Aa, cur, 0, 0); G_RDB(Bk0, cur, 0);
;             if (t + 1 < nt) G_STAGE_B(Bb, cur ^ 1, t + 1);
;             else if (has_next) G_STAGE_B(Bb2, cur ^ 1, 0);
;             G_SB0();
;             if (t > 0) G_MMA(Ab_, Bk1, 1);
;             G_SB0();
;             if (t + 1 < nt) G_STAGE_A(Ab, cur ^ 1, t + 1);
;             else if (has_next) G_STAGE_A(Ab2, cur ^ 1, 0);
;             G_RDA(Ab_, cur, 0, 1);
;             G_MMA(Aa, Bk0, 0); G_SB0();
;             G_RDA(Aa, cur, 1, 0); G_RDB(Bk1, cur, 1);
;             G_MMA(Ab_, Bk0, 1); G_SB0();
;             G_RDA(Ab_, cur, 1, 1);
;             G_MMA(Aa, Bk1, 0); G_SB0();
;             asm volatile("s_waitcnt lgkmcnt(0)" ::: "memory");
;             WAIT_V0(); __syncthreads();
;         }
	v_mfma_f32_16x16x32_bf16 v[0:3], v[204:207], v[176:179], v[0:3]
	v_mfma_f32_16x16x32_bf16 v[4:7], v[210:213], v[176:179], v[4:7]
	v_mfma_f32_16x16x32_bf16 v[8:11], v[214:217], v[176:179], v[8:11]
	v_mfma_f32_16x16x32_bf16 v[12:15], v[222:225], v[176:179], v[12:15]
	v_mfma_f32_16x16x32_bf16 v[16:19], v[204:207], v[180:183], v[16:19]
	v_mfma_f32_16x16x32_bf16 v[20:23], v[210:213], v[180:183], v[20:23]
	v_mfma_f32_16x16x32_bf16 v[24:27], v[214:217], v[180:183], v[24:27]
	v_mfma_f32_16x16x32_bf16 v[28:31], v[222:225], v[180:183], v[28:31]
	v_mfma_f32_16x16x32_bf16 v[32:35], v[204:207], v[184:187], v[32:35]
	v_mfma_f32_16x16x32_bf16 v[36:39], v[210:213], v[184:187], v[36:39]
	v_mfma_f32_16x16x32_bf16 v[40:43], v[214:217], v[184:187], v[40:43]
	v_mfma_f32_16x16x32_bf16 v[44:47], v[222:225], v[184:187], v[44:47]
	v_mfma_f32_16x16x32_bf16 v[48:51], v[204:207], v[188:191], v[48:51]
	v_mfma_f32_16x16x32_bf16 v[52:55], v[210:213], v[188:191], v[52:55]
	v_mfma_f32_16x16x32_bf16 v[56:59], v[214:217], v[188:191], v[56:59]
	v_mfma_f32_16x16x32_bf16 v[60:63], v[222:225], v[188:191], v[60:63]
	s_setprio 0
	ds_read_b128 v[176:179], v221 offset:1024
	ds_read_b128 v[180:183], v221 offset:3072
	ds_read_b128 v[184:187], v221 offset:5120
	ds_read_b128 v[188:191], v221 offset:7168
	ds_read_b128 v[64:67], v226 offset:33792
	ds_read_b128 v[68:71], v226 offset:35840
	ds_read_b128 v[76:79], v226 offset:37888
	ds_read_b128 v[72:75], v226 offset:39936
	s_setprio 1
	s_waitcnt lgkmcnt(8)
	v_mfma_f32_16x16x32_bf16 v[128:131], v[204:207], v[144:147], v[128:131]
	v_mfma_f32_16x16x32_bf16 v[124:127], v[210:213], v[144:147], v[124:127]
	v_mfma_f32_16x16x32_bf16 v[120:123], v[214:217], v[144:147], v[120:123]
	v_mfma_f32_16x16x32_bf16 v[116:119], v[222:225], v[144:147], v[116:119]
	v_mfma_f32_16x16x32_bf16 v[112:115], v[204:207], v[148:151], v[112:115]
	v_mfma_f32_16x16x32_bf16 v[108:111], v[210:213], v[148:151], v[108:111]
	v_mfma_f32_16x16x32_bf16 v[104:107], v[214:217], v[148:151], v[104:107]
	v_mfma_f32_16x16x32_bf16 v[100:103], v[222:225], v[148:151], v[100:103]
	v_mfma_f32_16x16x32_bf16 v[96:99], v[204:207], v[152:155], v[96:99]
	v_mfma_f32_16x16x32_bf16 v[92:95], v[210:213], v[152:155], v[92:95]
	v_mfma_f32_16x16x32_bf16 v[88:91], v[214:217], v[152:155], v[88:91]
	v_mfma_f32_16x16x32_bf16 v[84:87], v[222:225], v[152:155], v[84:87]
	v_mfma_f32_16x16x32_bf16 v[132:135], v[204:207], v[156:159], v[132:135]
	v_mfma_f32_16x16x32_bf16 v[136:139], v[210:213], v[156:159], v[136:139]
	v_mfma_f32_16x16x32_bf16 v[140:143], v[214:217], v[156:159], v[140:143]
	v_mfma_f32_16x16x32_bf16 v[80:83], v[222:225], v[156:159], v[80:83]
	s_setprio 0
	ds_read_b128 v[156:159], v221 offset:9216
	ds_read_b128 v[152:155], v221 offset:11264
	ds_read_b128 v[148:151], v221 offset:13312
	ds_read_b128 v[144:147], v221 offset:15360
	s_setprio 1
	s_waitcnt lgkmcnt(4)
	v_mfma_f32_16x16x32_bf16 v[0:3], v[64:67], v[176:179], v[0:3]
	v_mfma_f32_16x16x32_bf16 v[4:7], v[68:71], v[176:179], v[4:7]
	v_mfma_f32_16x16x32_bf16 v[8:11], v[76:79], v[176:179], v[8:11]
	v_mfma_f32_16x16x32_bf16 v[12:15], v[72:75], v[176:179], v[12:15]
	v_mfma_f32_16x16x32_bf16 v[16:19], v[64:67], v[180:183], v[16:19]
	v_mfma_f32_16x16x32_bf16 v[20:23], v[68:71], v[180:183], v[20:23]
	v_mfma_f32_16x16x32_bf16 v[24:27], v[76:79], v[180:183], v[24:27]
	v_mfma_f32_16x16x32_bf16 v[28:31], v[72:75], v[180:183], v[28:31]
	v_mfma_f32_16x16x32_bf16 v[32:35], v[64:67], v[184:187], v[32:35]
	v_mfma_f32_16x16x32_bf16 v[36:39], v[68:71], v[184:187], v[36:39]
	v_mfma_f32_16x16x32_bf16 v[40:43], v[76:79], v[184:187], v[40:43]
	v_mfma_f32_16x16x32_bf16 v[44:47], v[72:75], v[184:187], v[44:47]
	v_mfma_f32_16x16x32_bf16 v[48:51], v[64:67], v[188:191], v[48:51]
	v_mfma_f32_16x16x32_bf16 v[52:55], v[68:71], v[188:191], v[52:55]
	v_mfma_f32_16x16x32_bf16 v[56:59], v[76:79], v[188:191], v[56:59]
	v_mfma_f32_16x16x32_bf16 v[60:63], v[72:75], v[188:191], v[60:63]
	s_setprio 0
	s_waitcnt lgkmcnt(0)
	s_add_u32 s52, s52, 0x80
	s_addc_u32 s53, s53, 0
	s_add_u32 s64, s64, 0x80
	s_addc_u32 s65, s65, 0
	s_add_u32 s4, s4, 0x80
	s_addc_u32 s5, s5, 0
	s_add_i32 s8, s8, 0x10000
	s_and_b32 s9, s8, 0x10000
	v_add_u32_e32 v221, s9, v218
	v_or_b32_e32 v226, s9, v219
	s_xor_b32 s9, s9, 0x10000
	s_add_u32 s9, s9, s30
	s_cmpk_eq_i32 s4, 0x700
	s_waitcnt vmcnt(0)
	s_barrier
	s_cbranch_scc0 .LBB0_264
	v_readlane_b32 s52, v255, 12
	v_readlane_b32 s53, v255, 13
	v_readlane_b32 s64, v255, 14
	v_readlane_b32 s65, v255, 15
	v_readlane_b32 s30, v255, 16
	v_add_u32_e32 v160, 0x10000, v218
	v_add_u32_e32 v161, 0x10800, v218
	ds_read_b128 v[188:191], v160
	ds_read_b128 v[180:183], v161
	v_add_u32_e32 v160, 0x11000, v218
	v_add_u32_e32 v161, 0x11800, v218
	ds_read_b128 v[184:187], v160
	ds_read_b128 v[176:179], v161
	v_or_b32_e32 v160, 0x18000, v219
	v_add_u32_e32 v164, 0x18800, v219
	v_add_u32_e32 v168, 0x19000, v219
	v_add_u32_e32 v172, 0x19800, v219
	ds_read_b128 v[160:163], v160
	ds_read_b128 v[164:167], v164
	ds_read_b128 v[168:171], v168
	ds_read_b128 v[172:175], v172
	s_ashr_i32 s43, s42, 31
	v_cndmask_b32_e64 v200, 0, 1, s[6:7]
	v_cmp_ne_u32_e64 s[4:5], 1, v200
	s_andn2_b64 vcc, exec, s[6:7]
	s_lshl_b64 s[46:47], s[42:43], 19
	s_cbranch_vccnz .LBB0_267
	s_add_u32 s6, s14, s46
	s_addc_u32 s7, s15, s47
	v_add_u32_e32 v212, 0x8000, v220
	v_lshl_add_u64 v[200:201], s[6:7], 0, v[192:193]
	v_lshl_add_u64 v[204:205], s[6:7], 0, v[194:195]
	v_lshl_add_u64 v[206:207], s[6:7], 0, v[196:197]
	v_lshl_add_u64 v[210:211], s[6:7], 0, v[198:199]
	v_add_u32_e32 v215, 0xa000, v220
	v_readfirstlane_b32 s6, v212
	v_add_u32_e32 v214, 0xc000, v220
	s_mov_b32 m0, s6
	v_readfirstlane_b32 s6, v215
	v_add_u32_e32 v213, 0xe000, v220
	global_load_lds_dwordx4 v[200:201], off
	s_mov_b32 m0, s6
	v_readfirstlane_b32 s6, v214
	global_load_lds_dwordx4 v[204:205], off
	s_mov_b32 m0, s6
	v_readfirstlane_b32 s6, v213
	global_load_lds_dwordx4 v[206:207], off
	s_mov_b32 m0, s6
	s_nop 0
	global_load_lds_dwordx4 v[210:211], off
